# cross-tile prefetch in up1/in/up2: next tile's first two K-tiles (16 LDS-DMA loads) issued before the epilogue; later tiles enter via load-free prologue copy + peeled first loop iteration with store-a
# speedup vs baseline: 1.0244x; 1.0072x over previous
.LBB0_110:
	s_or_b64 exec, exec, s[6:7]
	s_add_i32 s36, s10, s74
	s_cmpk_gt_i32 s36, 0x57f
	s_cbranch_scc1 .Lt2_skip_up1
	s_lshl_b32 s37, s36, 3
	s_and_b32 s37, s37, 56
	s_bfe_u32 s43, s36, 0x30003
	s_or_b32 s37, s37, s43
	s_lshl_b32 s37, s37, 19
	v_readlane_b32 s38, v253, 47
	v_readlane_b32 s39, v253, 48
	s_add_u32 s38, s38, s37
	s_addc_u32 s39, s39, 0
	s_ashr_i32 s43, s36, 6
	s_lshl_b32 s43, s43, 19
	s_add_u32 s40, s21, s43
	s_addc_u32 s41, s22, 0
	v_lshrrev_b32_e32 v243, 7, v154
	v_bfe_u32 v244, v154, 2, 4
	v_lshl_add_u32 v243, v243, 4, v244
	v_bfe_u32 v244, v154, 5, 1
	v_lshlrev_b32_e32 v244, 1, v244
	v_and_b32_e32 v245, 3, v154
	v_xor_b32_e32 v244, v244, v245
	v_lshlrev_b32_e32 v244, 4, v244
	v_bfe_u32 v245, v154, 6, 1
	v_lshl_or_b32 v244, v245, 6, v244
	v_lshl_or_b32 v242, v243, 11, v244
	v_lshrrev_b32_e32 v245, 6, v154
	v_lshlrev_b32_e32 v245, 10, v245
	s_nop 0
	v_readfirstlane_b32 s42, v245
	s_add_u32 m0, s42, 0x8000
	s_nop 0
	global_load_lds_dwordx4 v242, s[40:41]
	s_add_u32 m0, s42, 0xa000
	s_add_u32 s40, s40, 0x20000
	s_addc_u32 s41, s41, 0
	global_load_lds_dwordx4 v242, s[40:41]
	s_add_u32 m0, s42, 0x0
	s_nop 0
	global_load_lds_dwordx4 v242, s[38:39]
	s_add_u32 m0, s42, 0x2000
	s_add_u32 s38, s38, 0x20000
	s_addc_u32 s39, s39, 0
	global_load_lds_dwordx4 v242, s[38:39]
	s_add_u32 m0, s42, 0xc000
	s_add_u32 s40, s40, 0x20000
	s_addc_u32 s41, s41, 0
	global_load_lds_dwordx4 v242, s[40:41]
	s_add_u32 m0, s42, 0xe000
	s_add_u32 s40, s40, 0x20000
	s_addc_u32 s41, s41, 0
	global_load_lds_dwordx4 v242, s[40:41]
	s_add_u32 m0, s42, 0x4000
	s_add_u32 s38, s38, 0x20000
	s_addc_u32 s39, s39, 0
	global_load_lds_dwordx4 v242, s[38:39]
	s_add_u32 m0, s42, 0x6000
	s_add_u32 s38, s38, 0x20000
	s_addc_u32 s39, s39, 0
	global_load_lds_dwordx4 v242, s[38:39]
	s_add_u32 m0, s42, 0x18000
	s_sub_u32 s40, s40, 0x5ff80
	s_subb_u32 s41, s41, 0
	global_load_lds_dwordx4 v242, s[40:41]
	s_add_u32 m0, s42, 0x1a000
	s_add_u32 s40, s40, 0x20000
	s_addc_u32 s41, s41, 0
	global_load_lds_dwordx4 v242, s[40:41]
	s_add_u32 m0, s42, 0x10000
	s_sub_u32 s38, s38, 0x5ff80
	s_subb_u32 s39, s39, 0
	global_load_lds_dwordx4 v242, s[38:39]
	s_add_u32 m0, s42, 0x12000
	s_add_u32 s38, s38, 0x20000
	s_addc_u32 s39, s39, 0
	global_load_lds_dwordx4 v242, s[38:39]
	s_add_u32 m0, s42, 0x1c000
	s_add_u32 s40, s40, 0x20000
	s_addc_u32 s41, s41, 0
	global_load_lds_dwordx4 v242, s[40:41]
	s_add_u32 m0, s42, 0x1e000
	s_add_u32 s40, s40, 0x20000
	s_addc_u32 s41, s41, 0
	global_load_lds_dwordx4 v242, s[40:41]
	s_add_u32 m0, s42, 0x14000
	s_add_u32 s38, s38, 0x20000
	s_addc_u32 s39, s39, 0
	global_load_lds_dwordx4 v242, s[38:39]
	s_add_u32 m0, s42, 0x16000
	s_add_u32 s38, s38, 0x20000
	s_addc_u32 s39, s39, 0
	global_load_lds_dwordx4 v242, s[38:39]
.Lt2_skip_up1:
	v_mov_b32_e32 v128, v154
	v_mul_f32_e32 v130, 0xbfb8aa3b, v121
	v_ashrrev_i32_e32 v129, 2, v128
	v_and_b32_e32 v129, 0xffffffc0, v129
	v_lshl_add_u32 v129, s12, 8, v129
	v_and_or_b32 v132, v128, 15, v129
	v_mul_f32_e32 v129, 0xbfb8aa3b, v120
	v_exp_f32_e32 v129, v129
	v_exp_f32_e32 v130, v130
	v_lshrrev_b32_e32 v131, 1, v128
	s_add_i32 s10, s10, s74
	v_add_f32_e32 v128, 1.0, v129
	v_add_f32_e32 v129, 1.0, v130
	v_rcp_f32_e32 v128, v128
	v_rcp_f32_e32 v129, v129
	v_and_b32_e32 v130, 0x78, v131
	v_lshl_or_b32 v130, s4, 7, v130
	v_readlane_b32 s4, v253, 49
	v_pk_mul_f32 v[120:121], v[120:121], v[128:129]
	v_mul_f32_e32 v128, 0xbfb8aa3b, v122
	v_mul_f32_e32 v129, 0xbfb8aa3b, v123
	v_exp_f32_e32 v128, v128
	v_exp_f32_e32 v129, v129
	v_pk_mul_f32 v[120:121], v[120:121], v[124:125]
	v_readlane_b32 s5, v253, 50
	v_add_f32_e32 v124, 1.0, v128
	v_add_f32_e32 v125, 1.0, v129
	v_mul_f32_e32 v128, 0xbfb8aa3b, v112
	v_mul_f32_e32 v129, 0xbfb8aa3b, v113
	v_rcp_f32_e32 v124, v124
	v_rcp_f32_e32 v125, v125
	v_exp_f32_e32 v128, v128
	v_exp_f32_e32 v129, v129
	v_ashrrev_i32_e32 v131, 31, v130
	v_pk_mul_f32 v[122:123], v[122:123], v[124:125]
	v_add_f32_e32 v124, 1.0, v128
	v_add_f32_e32 v125, 1.0, v129
	v_mul_f32_e32 v128, 0xbfb8aa3b, v114
	v_mul_f32_e32 v129, 0xbfb8aa3b, v115
	v_exp_f32_e32 v128, v128
	v_exp_f32_e32 v129, v129
	v_rcp_f32_e32 v124, v124
	v_rcp_f32_e32 v125, v125
	v_add_f32_e32 v128, 1.0, v128
	v_add_f32_e32 v129, 1.0, v129
	v_rcp_f32_e32 v128, v128
	v_rcp_f32_e32 v129, v129
	v_pk_mul_f32 v[112:113], v[112:113], v[124:125]
	v_pk_mul_f32 v[122:123], v[122:123], v[126:127]
	v_pk_mul_f32 v[112:113], v[112:113], v[116:117]
	v_pk_mul_f32 v[114:115], v[114:115], v[128:129]
	v_cvt_pk_bf16_f32 v116, v120, v121
	v_pk_mul_f32 v[114:115], v[114:115], v[118:119]
	v_cvt_pk_bf16_f32 v118, v112, v113
	v_cvt_pk_bf16_f32 v119, v114, v115
	v_mul_f32_e32 v114, 0xbfb8aa3b, v104
	v_exp_f32_e32 v114, v114
	v_mul_f32_e32 v115, 0xbfb8aa3b, v105
	v_exp_f32_e32 v115, v115
	v_mov_b64_e32 v[112:113], s[4:5]
	v_add_f32_e32 v114, 1.0, v114
	v_rcp_f32_e32 v120, v114
	v_add_f32_e32 v114, 1.0, v115
	v_mad_i64_i32 v[112:113], s[4:5], v132, s33, v[112:113]
	v_rcp_f32_e32 v121, v114
	v_lshlrev_b64 v[114:115], 1, v[130:131]
	v_cvt_pk_bf16_f32 v117, v122, v123
	v_lshl_add_u64 v[112:113], v[112:113], 0, v[114:115]
	global_store_dwordx4 v[112:113], v[116:119], off
	v_pk_mul_f32 v[104:105], v[104:105], v[120:121]
	v_readlane_b32 s4, v253, 51
	v_mul_f32_e32 v116, 0xbfb8aa3b, v106
	v_mul_f32_e32 v117, 0xbfb8aa3b, v107
	v_exp_f32_e32 v116, v116
	v_exp_f32_e32 v117, v117
	v_pk_mul_f32 v[104:105], v[104:105], v[108:109]
	v_readlane_b32 s5, v253, 52
	v_add_f32_e32 v108, 1.0, v116
	v_add_f32_e32 v109, 1.0, v117
	v_mul_f32_e32 v116, 0xbfb8aa3b, v96
	v_mul_f32_e32 v117, 0xbfb8aa3b, v97
	v_rcp_f32_e32 v108, v108
	v_rcp_f32_e32 v109, v109
	v_exp_f32_e32 v116, v116
	v_exp_f32_e32 v117, v117
	s_add_i32 s11, s11, s20
	v_pk_mul_f32 v[106:107], v[106:107], v[108:109]
	v_add_f32_e32 v108, 1.0, v116
	v_add_f32_e32 v109, 1.0, v117
	v_mul_f32_e32 v116, 0xbfb8aa3b, v98
	v_mul_f32_e32 v117, 0xbfb8aa3b, v99
	v_exp_f32_e32 v116, v116
	v_exp_f32_e32 v117, v117
	v_rcp_f32_e32 v108, v108
	v_rcp_f32_e32 v109, v109
	v_add_f32_e32 v116, 1.0, v116
	v_add_f32_e32 v117, 1.0, v117
	v_rcp_f32_e32 v116, v116
	v_rcp_f32_e32 v117, v117
	v_pk_mul_f32 v[96:97], v[96:97], v[108:109]
	v_pk_mul_f32 v[106:107], v[106:107], v[110:111]
	v_pk_mul_f32 v[96:97], v[96:97], v[100:101]
	v_pk_mul_f32 v[98:99], v[98:99], v[116:117]
	v_cvt_pk_bf16_f32 v100, v96, v97
	v_pk_mul_f32 v[102:103], v[98:99], v[102:103]
	v_mul_f32_e32 v96, 0xbfb8aa3b, v88
	v_cvt_pk_bf16_f32 v101, v102, v103
	v_exp_f32_e32 v102, v96
	v_mul_f32_e32 v96, 0xbfb8aa3b, v89
	v_exp_f32_e32 v103, v96
	v_mov_b64_e32 v[96:97], s[4:5]
	v_mad_i64_i32 v[96:97], s[4:5], v132, s33, v[96:97]
	v_cvt_pk_bf16_f32 v98, v104, v105
	v_cvt_pk_bf16_f32 v99, v106, v107
	v_add_f32_e32 v102, 1.0, v102
	v_add_f32_e32 v103, 1.0, v103
	v_lshl_add_u64 v[96:97], v[96:97], 0, v[114:115]
	v_rcp_f32_e32 v102, v102
	v_rcp_f32_e32 v103, v103
	global_store_dwordx4 v[96:97], v[98:101], off
	v_readlane_b32 s4, v253, 53
	v_readlane_b32 s5, v253, 54
	v_mul_f32_e32 v98, 0xbfb8aa3b, v90
	v_mul_f32_e32 v99, 0xbfb8aa3b, v91
	v_exp_f32_e32 v98, v98
	v_exp_f32_e32 v99, v99
	v_pk_mul_f32 v[88:89], v[88:89], v[102:103]
	s_cmpk_lt_i32 s10, 0x580
	v_pk_mul_f32 v[88:89], v[88:89], v[92:93]
	v_add_f32_e32 v92, 1.0, v98
	v_add_f32_e32 v93, 1.0, v99
	v_mul_f32_e32 v98, 0xbfb8aa3b, v80
	v_mul_f32_e32 v99, 0xbfb8aa3b, v81
	v_rcp_f32_e32 v92, v92
	v_rcp_f32_e32 v93, v93
	v_exp_f32_e32 v98, v98
	v_exp_f32_e32 v99, v99
	v_pk_mul_f32 v[90:91], v[90:91], v[92:93]
	v_add_f32_e32 v92, 1.0, v98
	v_add_f32_e32 v93, 1.0, v99
	v_mul_f32_e32 v98, 0xbfb8aa3b, v82
	v_mul_f32_e32 v99, 0xbfb8aa3b, v83
	v_exp_f32_e32 v98, v98
	v_exp_f32_e32 v99, v99
	v_rcp_f32_e32 v92, v92
	v_rcp_f32_e32 v93, v93
	v_add_f32_e32 v98, 1.0, v98
	v_add_f32_e32 v99, 1.0, v99
	v_rcp_f32_e32 v98, v98
	v_rcp_f32_e32 v99, v99
	v_pk_mul_f32 v[80:81], v[80:81], v[92:93]
	v_pk_mul_f32 v[90:91], v[90:91], v[94:95]
	v_pk_mul_f32 v[80:81], v[80:81], v[84:85]
	v_pk_mul_f32 v[82:83], v[82:83], v[98:99]
	v_cvt_pk_bf16_f32 v84, v80, v81
	v_pk_mul_f32 v[86:87], v[82:83], v[86:87]
	v_mul_f32_e32 v80, 0xbfb8aa3b, v72
	v_cvt_pk_bf16_f32 v85, v86, v87
	v_exp_f32_e32 v86, v80
	v_mul_f32_e32 v80, 0xbfb8aa3b, v73
	v_exp_f32_e32 v87, v80
	v_mov_b64_e32 v[80:81], s[4:5]
	v_mad_i64_i32 v[80:81], s[4:5], v132, s33, v[80:81]
	v_cvt_pk_bf16_f32 v82, v88, v89
	v_cvt_pk_bf16_f32 v83, v90, v91
	v_add_f32_e32 v86, 1.0, v86
	v_add_f32_e32 v87, 1.0, v87
	v_lshl_add_u64 v[80:81], v[80:81], 0, v[114:115]
	v_rcp_f32_e32 v86, v86
	v_rcp_f32_e32 v87, v87
	global_store_dwordx4 v[80:81], v[82:85], off
	v_readlane_b32 s4, v253, 55
	v_readlane_b32 s5, v253, 56
	v_mul_f32_e32 v82, 0xbfb8aa3b, v74
	v_mul_f32_e32 v83, 0xbfb8aa3b, v75
	v_exp_f32_e32 v82, v82
	v_exp_f32_e32 v83, v83
	v_pk_mul_f32 v[72:73], v[72:73], v[86:87]
	s_nop 0
	v_pk_mul_f32 v[72:73], v[72:73], v[76:77]
	v_add_f32_e32 v76, 1.0, v82
	v_add_f32_e32 v77, 1.0, v83
	v_mul_f32_e32 v82, 0xbfb8aa3b, v64
	v_mul_f32_e32 v83, 0xbfb8aa3b, v65
	v_rcp_f32_e32 v76, v76
	v_rcp_f32_e32 v77, v77
	v_exp_f32_e32 v82, v82
	v_exp_f32_e32 v83, v83
	v_pk_mul_f32 v[74:75], v[74:75], v[76:77]
	v_add_f32_e32 v76, 1.0, v82
	v_add_f32_e32 v77, 1.0, v83
	v_mul_f32_e32 v82, 0xbfb8aa3b, v66
	v_mul_f32_e32 v83, 0xbfb8aa3b, v67
	v_exp_f32_e32 v82, v82
	v_exp_f32_e32 v83, v83
	v_rcp_f32_e32 v76, v76
	v_rcp_f32_e32 v77, v77
	v_add_f32_e32 v82, 1.0, v82
	v_add_f32_e32 v83, 1.0, v83
	v_rcp_f32_e32 v82, v82
	v_rcp_f32_e32 v83, v83
	v_pk_mul_f32 v[64:65], v[64:65], v[76:77]
	v_pk_mul_f32 v[74:75], v[74:75], v[78:79]
	v_pk_mul_f32 v[64:65], v[64:65], v[68:69]
	v_pk_mul_f32 v[66:67], v[66:67], v[82:83]
	v_cvt_pk_bf16_f32 v68, v64, v65
	v_pk_mul_f32 v[70:71], v[66:67], v[70:71]
	v_mul_f32_e32 v64, 0xbfb8aa3b, v60
	v_cvt_pk_bf16_f32 v69, v70, v71
	v_exp_f32_e32 v70, v64
	v_mul_f32_e32 v64, 0xbfb8aa3b, v61
	v_exp_f32_e32 v71, v64
	v_mov_b64_e32 v[64:65], s[4:5]
	v_mad_i64_i32 v[64:65], s[4:5], v132, s33, v[64:65]
	v_cvt_pk_bf16_f32 v66, v72, v73
	v_cvt_pk_bf16_f32 v67, v74, v75
	v_add_f32_e32 v70, 1.0, v70
	v_add_f32_e32 v71, 1.0, v71
	v_lshl_add_u64 v[64:65], v[64:65], 0, v[114:115]
	v_rcp_f32_e32 v70, v70
	v_rcp_f32_e32 v71, v71
	global_store_dwordx4 v[64:65], v[66:69], off
	s_mov_b32 s4, 0xb0000
	v_pk_mul_f32 v[60:61], v[60:61], v[70:71]
	v_mul_f32_e32 v66, 0xbfb8aa3b, v62
	v_mul_f32_e32 v67, 0xbfb8aa3b, v63
	v_exp_f32_e32 v66, v66
	v_exp_f32_e32 v67, v67
	v_pk_mul_f32 v[56:57], v[60:61], v[56:57]
	v_add_f32_e32 v60, 1.0, v66
	v_add_f32_e32 v61, 1.0, v67
	v_mul_f32_e32 v66, 0xbfb8aa3b, v48
	v_mul_f32_e32 v67, 0xbfb8aa3b, v49
	v_rcp_f32_e32 v60, v60
	v_rcp_f32_e32 v61, v61
	v_exp_f32_e32 v66, v66
	v_exp_f32_e32 v67, v67
	v_pk_mul_f32 v[60:61], v[62:63], v[60:61]
	v_add_f32_e32 v62, 1.0, v66
	v_add_f32_e32 v63, 1.0, v67
	v_mul_f32_e32 v66, 0xbfb8aa3b, v50
	v_mul_f32_e32 v67, 0xbfb8aa3b, v51
	v_exp_f32_e32 v66, v66
	v_exp_f32_e32 v67, v67
	v_rcp_f32_e32 v62, v62
	v_rcp_f32_e32 v63, v63
	v_add_f32_e32 v66, 1.0, v66
	v_add_f32_e32 v67, 1.0, v67
	v_rcp_f32_e32 v66, v66
	v_rcp_f32_e32 v67, v67
	v_pk_mul_f32 v[48:49], v[48:49], v[62:63]
	v_pk_mul_f32 v[58:59], v[60:61], v[58:59]
	v_pk_mul_f32 v[52:53], v[48:49], v[52:53]
	v_pk_mul_f32 v[48:49], v[50:51], v[66:67]
	v_mul_f32_e32 v51, 0xbfb8aa3b, v44
	v_cvt_pk_bf16_f32 v50, v52, v53
	v_exp_f32_e32 v52, v51
	v_mul_f32_e32 v51, 0xbfb8aa3b, v45
	v_exp_f32_e32 v53, v51
	v_pk_mul_f32 v[54:55], v[48:49], v[54:55]
	v_cvt_pk_bf16_f32 v48, v56, v57
	v_cvt_pk_bf16_f32 v51, v54, v55
	v_add_co_u32_e32 v54, vcc, s4, v112
	v_cvt_pk_bf16_f32 v49, v58, v59
	v_add_f32_e32 v52, 1.0, v52
	v_add_f32_e32 v53, 1.0, v53
	v_addc_co_u32_e32 v55, vcc, 0, v113, vcc
	v_rcp_f32_e32 v52, v52
	v_rcp_f32_e32 v53, v53
	global_store_dwordx4 v[54:55], v[48:51], off
	v_pk_mul_f32 v[44:45], v[44:45], v[52:53]
	s_nop 0
	v_mul_f32_e32 v48, 0xbfb8aa3b, v46
	v_mul_f32_e32 v49, 0xbfb8aa3b, v47
	v_exp_f32_e32 v48, v48
	v_exp_f32_e32 v49, v49
	v_pk_mul_f32 v[40:41], v[44:45], v[40:41]
	v_add_f32_e32 v44, 1.0, v48
	v_add_f32_e32 v45, 1.0, v49
	v_mul_f32_e32 v48, 0xbfb8aa3b, v32
	v_mul_f32_e32 v49, 0xbfb8aa3b, v33
	v_rcp_f32_e32 v44, v44
	v_rcp_f32_e32 v45, v45
	v_exp_f32_e32 v48, v48
	v_exp_f32_e32 v49, v49
	v_pk_mul_f32 v[44:45], v[46:47], v[44:45]
	v_add_f32_e32 v46, 1.0, v48
	v_add_f32_e32 v47, 1.0, v49
	v_mul_f32_e32 v48, 0xbfb8aa3b, v34
	v_mul_f32_e32 v49, 0xbfb8aa3b, v35
	v_exp_f32_e32 v48, v48
	v_exp_f32_e32 v49, v49
	v_rcp_f32_e32 v46, v46
	v_rcp_f32_e32 v47, v47
	v_add_f32_e32 v48, 1.0, v48
	v_add_f32_e32 v49, 1.0, v49
	v_rcp_f32_e32 v48, v48
	v_rcp_f32_e32 v49, v49
	v_pk_mul_f32 v[32:33], v[32:33], v[46:47]
	v_pk_mul_f32 v[42:43], v[44:45], v[42:43]
	v_pk_mul_f32 v[36:37], v[32:33], v[36:37]
	v_pk_mul_f32 v[32:33], v[34:35], v[48:49]
	v_mul_f32_e32 v35, 0xbfb8aa3b, v28
	v_cvt_pk_bf16_f32 v34, v36, v37
	v_exp_f32_e32 v36, v35
	v_mul_f32_e32 v35, 0xbfb8aa3b, v29
	v_exp_f32_e32 v37, v35
	v_pk_mul_f32 v[38:39], v[32:33], v[38:39]
	v_cvt_pk_bf16_f32 v32, v40, v41
	v_cvt_pk_bf16_f32 v35, v38, v39
	v_add_co_u32_e32 v38, vcc, s4, v96
	v_cvt_pk_bf16_f32 v33, v42, v43
	v_add_f32_e32 v36, 1.0, v36
	v_add_f32_e32 v37, 1.0, v37
	v_addc_co_u32_e32 v39, vcc, 0, v97, vcc
	v_rcp_f32_e32 v36, v36
	v_rcp_f32_e32 v37, v37
	global_store_dwordx4 v[38:39], v[32:35], off
	v_pk_mul_f32 v[28:29], v[28:29], v[36:37]
	s_nop 0
	v_mul_f32_e32 v32, 0xbfb8aa3b, v30
	v_mul_f32_e32 v33, 0xbfb8aa3b, v31
	v_exp_f32_e32 v32, v32
	v_exp_f32_e32 v33, v33
	v_pk_mul_f32 v[24:25], v[28:29], v[24:25]
	v_add_f32_e32 v28, 1.0, v32
	v_add_f32_e32 v29, 1.0, v33
	v_mul_f32_e32 v32, 0xbfb8aa3b, v16
	v_mul_f32_e32 v33, 0xbfb8aa3b, v17
	v_rcp_f32_e32 v28, v28
	v_rcp_f32_e32 v29, v29
	v_exp_f32_e32 v32, v32
	v_exp_f32_e32 v33, v33
	v_pk_mul_f32 v[28:29], v[30:31], v[28:29]
	v_add_f32_e32 v30, 1.0, v32
	v_add_f32_e32 v31, 1.0, v33
	v_mul_f32_e32 v32, 0xbfb8aa3b, v18
	v_mul_f32_e32 v33, 0xbfb8aa3b, v19
	v_exp_f32_e32 v32, v32
	v_exp_f32_e32 v33, v33
	v_rcp_f32_e32 v30, v30
	v_rcp_f32_e32 v31, v31
	v_add_f32_e32 v32, 1.0, v32
	v_add_f32_e32 v33, 1.0, v33
	v_rcp_f32_e32 v32, v32
	v_rcp_f32_e32 v33, v33
	v_pk_mul_f32 v[16:17], v[16:17], v[30:31]
	v_pk_mul_f32 v[26:27], v[28:29], v[26:27]
	v_pk_mul_f32 v[20:21], v[16:17], v[20:21]
	v_pk_mul_f32 v[16:17], v[18:19], v[32:33]
	v_mul_f32_e32 v19, 0xbfb8aa3b, v12
	v_cvt_pk_bf16_f32 v18, v20, v21
	v_exp_f32_e32 v20, v19
	v_mul_f32_e32 v19, 0xbfb8aa3b, v13
	v_exp_f32_e32 v21, v19
	v_pk_mul_f32 v[22:23], v[16:17], v[22:23]
	v_cvt_pk_bf16_f32 v16, v24, v25
	v_cvt_pk_bf16_f32 v19, v22, v23
	v_add_co_u32_e32 v22, vcc, s4, v80
	v_cvt_pk_bf16_f32 v17, v26, v27
	v_add_f32_e32 v20, 1.0, v20
	v_add_f32_e32 v21, 1.0, v21
	v_addc_co_u32_e32 v23, vcc, 0, v81, vcc
	v_rcp_f32_e32 v20, v20
	v_rcp_f32_e32 v21, v21
	global_store_dwordx4 v[22:23], v[16:19], off
	v_pk_mul_f32 v[12:13], v[12:13], v[20:21]
	s_nop 0
	v_mul_f32_e32 v16, 0xbfb8aa3b, v14
	v_mul_f32_e32 v17, 0xbfb8aa3b, v15
	v_exp_f32_e32 v16, v16
	v_exp_f32_e32 v17, v17
	v_pk_mul_f32 v[8:9], v[12:13], v[8:9]
	v_add_f32_e32 v12, 1.0, v16
	v_add_f32_e32 v13, 1.0, v17
	v_mul_f32_e32 v16, 0xbfb8aa3b, v0
	v_mul_f32_e32 v17, 0xbfb8aa3b, v1
	v_rcp_f32_e32 v12, v12
	v_rcp_f32_e32 v13, v13
	v_exp_f32_e32 v16, v16
	v_exp_f32_e32 v17, v17
	v_pk_mul_f32 v[12:13], v[14:15], v[12:13]
	v_add_f32_e32 v14, 1.0, v16
	v_add_f32_e32 v15, 1.0, v17
	v_mul_f32_e32 v16, 0xbfb8aa3b, v2
	v_mul_f32_e32 v17, 0xbfb8aa3b, v3
	v_exp_f32_e32 v16, v16
	v_exp_f32_e32 v17, v17
	v_rcp_f32_e32 v14, v14
	v_rcp_f32_e32 v15, v15
	v_add_f32_e32 v16, 1.0, v16
	v_add_f32_e32 v17, 1.0, v17
	v_rcp_f32_e32 v16, v16
	v_rcp_f32_e32 v17, v17
	v_pk_mul_f32 v[0:1], v[0:1], v[14:15]
	v_pk_mul_f32 v[10:11], v[12:13], v[10:11]
	v_pk_mul_f32 v[4:5], v[0:1], v[4:5]
	v_pk_mul_f32 v[0:1], v[2:3], v[16:17]
	v_cvt_pk_bf16_f32 v2, v4, v5
	v_pk_mul_f32 v[6:7], v[0:1], v[6:7]
	v_add_co_u32_e32 v4, vcc, 0xb0000, v64
	v_cvt_pk_bf16_f32 v0, v8, v9
	v_cvt_pk_bf16_f32 v1, v10, v11
	v_cvt_pk_bf16_f32 v3, v6, v7
	v_addc_co_u32_e32 v5, vcc, 0, v65, vcc
	global_store_dwordx4 v[4:5], v[0:3], off
	s_cbranch_scc0 .LBB0_117
	s_branch .LP2_up1

.LP2_up1:
	s_lshl_b32 s4, s10, 3
	s_and_b32 s4, s4, 56
	s_bfe_u32 s5, s10, 0x30003
	v_mov_b32_e32 v134, v154
	s_or_b32 s12, s4, s5
	s_ashr_i32 s4, s10, 6
	v_ashrrev_i32_e32 v5, 6, v134
	v_lshrrev_b32_e32 v1, 4, v134
	v_ashrrev_i32_e32 v4, 3, v134
	v_lshrrev_b32_e32 v0, 2, v134
	v_and_b32_e32 v3, 3, v134
	s_lshl_b32 s5, s12, 19
	v_readlane_b32 s6, v253, 47
	v_bfi_b32 v0, -16, v4, v0
	v_lshlrev_b32_e32 v2, 5, v5
	v_bitop3_b32 v1, v1, v3, 2 bitop3:0x6c
	v_readlane_b32 s7, v253, 48
	s_add_u32 s8, s6, s5
	v_and_b32_e32 v2, 32, v2
	v_lshlrev_b32_e32 v3, 3, v1
	v_ashrrev_i32_e32 v1, 31, v0
	s_addc_u32 s9, s7, 0
	v_or_b32_e32 v11, v3, v2
	v_lshlrev_b64 v[0:1], 11, v[0:1]
	v_and_b32_e32 v9, 15, v134
	v_lshl_add_u64 v[6:7], s[8:9], 0, v[0:1]
	v_lshlrev_b32_e32 v136, 1, v11
	v_lshl_add_u64 v[128:129], v[6:7], 0, v[136:137]
	v_lshlrev_b32_e32 v6, 6, v9
	v_lshlrev_b32_e32 v9, 2, v134
	v_ashrrev_i32_e32 v8, 8, v134
	v_and_b32_e32 v10, 48, v134
	v_and_b32_e32 v9, 32, v9
	s_ashr_i32 s5, s4, 31
	v_or_b32_e32 v7, v6, v10
	v_bitop3_b32 v6, v6, v9, v10 bitop3:0x36
	v_lshlrev_b32_e32 v10, 13, v8
	v_lshlrev_b32_e32 v5, 12, v5
	s_lshl_b64 s[6:7], s[4:5], 19
	v_lshlrev_b32_e32 v146, 4, v134
	v_bitop3_b32 v144, v7, v10, v9 bitop3:0xde
	v_and_or_b32 v5, v5, s75, v6
	s_add_u32 s14, s21, s6
	v_add_u32_e32 v147, 0x10000, v146
	v_add_u32_e32 v135, 0x10000, v144
	v_or_b32_e32 v145, 0x8000, v5
	v_or_b32_e32 v139, 0x18000, v5
	s_addc_u32 s15, s22, s7
	v_lshl_add_u64 v[0:1], s[14:15], 0, v[0:1]
	v_add_u32_e32 v148, 0x8000, v146
	v_add_u32_e32 v149, 0xa000, v146
	v_readfirstlane_b32 s5, v148
	v_lshl_add_u64 v[0:1], v[0:1], 0, v[136:137]
	s_mov_b32 m0, s5
	s_mov_b64 s[8:9], 0x20000
	v_readfirstlane_b32 s5, v149
	v_lshl_add_u64 v[6:7], v[0:1], 0, s[8:9]
	s_mov_b32 m0, s5
	v_readfirstlane_b32 s5, v146
	v_add_u32_e32 v150, 0x2000, v146
	s_mov_b32 m0, s5
	v_readfirstlane_b32 s5, v150
	v_add_u32_e32 v151, 0xc000, v146
	v_lshl_add_u64 v[6:7], v[128:129], 0, s[8:9]
	s_mov_b32 m0, s5
	s_mov_b64 s[8:9], 0x40000
	v_readfirstlane_b32 s5, v151
	v_add_u32_e32 v152, 0xe000, v146
	v_lshl_add_u64 v[6:7], v[0:1], 0, s[8:9]
	s_mov_b32 m0, s5
	s_mov_b64 s[14:15], 0x60000
	v_readfirstlane_b32 s5, v152
	v_add_u32_e32 v153, 0x4000, v146
	v_lshl_add_u64 v[6:7], v[0:1], 0, s[14:15]
	s_mov_b32 m0, s5
	v_readfirstlane_b32 s5, v153
	v_add_u32_e32 v170, 0x6000, v146
	v_lshl_add_u64 v[6:7], v[128:129], 0, s[8:9]
	s_mov_b32 m0, s5
	v_readfirstlane_b32 s5, v170
	v_lshl_add_u64 v[6:7], v[128:129], 0, s[14:15]
	s_mov_b32 m0, s5
	v_cmp_eq_u32_e32 vcc, 1, v8
	s_and_saveexec_b64 s[8:9], vcc
	s_cbranch_execz .LP2_up1_113
	s_barrier
.LP2_up1_113:
	s_or_b64 exec, exec, s[8:9]
	s_lshr_b32 s5, s10, 3
	s_and_b32 s5, s5, 7
	s_lshl_b32 s8, s11, 19
	s_lshl_b32 s5, s5, 19
	s_and_b32 s8, s8, 0x1c00000
	v_add_u32_e32 v171, 0x8000, v147
	s_or_b32 s5, s8, s5
	s_mov_b64 s[14:15], 0x80
	v_readfirstlane_b32 s8, v171
	v_add_u32_e32 v172, 0xa000, v147
	v_and_b32_e32 v6, -16, v4
	v_lshl_add_u64 v[4:5], v[0:1], 0, s[14:15]
	s_mov_b32 m0, s8
	s_mov_b64 s[26:27], 0x20080
	v_readfirstlane_b32 s8, v172
	s_waitcnt vmcnt(20)
	s_barrier
	v_lshl_add_u64 v[4:5], v[0:1], 0, s[26:27]
	s_mov_b32 m0, s8
	v_readfirstlane_b32 s8, v147
	v_add_u32_e32 v173, 0x2000, v147
	v_lshl_add_u64 v[4:5], v[128:129], 0, s[14:15]
	s_mov_b32 m0, s8
	v_readfirstlane_b32 s8, v173
	v_lshl_add_u64 v[4:5], v[128:129], 0, s[26:27]
	s_mov_b32 m0, s8
	s_mov_b64 s[8:9], 0x40080
	v_add_u32_e32 v174, 0xc000, v147
	v_lshl_add_u64 v[4:5], v[0:1], 0, s[8:9]
	v_readfirstlane_b32 s8, v174
	s_mov_b32 m0, s8
	s_mov_b64 s[8:9], 0x60080
	v_add_u32_e32 v175, 0xe000, v147
	v_lshl_add_u64 v[0:1], v[0:1], 0, s[8:9]
	v_readfirstlane_b32 s8, v175
	s_mov_b32 m0, s8
	v_bfe_u32 v7, v134, 2, 4
	v_add_u32_e32 v0, v6, v7
	v_ashrrev_i32_e32 v1, 31, v0
	s_add_u32 s6, s21, s6
	v_lshlrev_b64 v[0:1], 11, v[0:1]
	s_addc_u32 s7, s22, s7
	v_lshl_add_u64 v[130:131], s[6:7], 0, v[0:1]
	s_add_u32 s6, s72, s5
	s_waitcnt vmcnt(16)
	s_addc_u32 s7, s73, 0
	v_lshl_add_u64 v[132:133], s[6:7], 0, v[0:1]
	v_mov_b32_e32 v0, 0
	v_add_lshl_u32 v136, v2, v3, 1
	s_mov_b32 s5, -2
	v_add_u32_e32 v177, 0x4000, v147
	v_add_u32_e32 v176, 0x6000, v147
	v_mov_b32_e32 v1, v0
	v_mov_b32_e32 v2, v0
	v_mov_b32_e32 v3, v0
	v_mov_b32_e32 v4, v0
	v_mov_b32_e32 v5, v0
	v_mov_b32_e32 v6, v0
	v_mov_b32_e32 v7, v0
	v_mov_b32_e32 v12, v0
	v_mov_b32_e32 v13, v0
	v_mov_b32_e32 v14, v0
	v_mov_b32_e32 v15, v0
	v_mov_b32_e32 v20, v0
	v_mov_b32_e32 v21, v0
	v_mov_b32_e32 v22, v0
	v_mov_b32_e32 v23, v0
	v_mov_b32_e32 v8, v0
	v_mov_b32_e32 v9, v0
	v_mov_b32_e32 v10, v0
	v_mov_b32_e32 v11, v0
	v_mov_b32_e32 v16, v0
	v_mov_b32_e32 v17, v0
	v_mov_b32_e32 v18, v0
	v_mov_b32_e32 v19, v0
	v_mov_b32_e32 v28, v0
	v_mov_b32_e32 v29, v0
	v_mov_b32_e32 v30, v0
	v_mov_b32_e32 v31, v0
	v_mov_b32_e32 v36, v0
	v_mov_b32_e32 v37, v0
	v_mov_b32_e32 v38, v0
	v_mov_b32_e32 v39, v0
	v_mov_b32_e32 v24, v0
	v_mov_b32_e32 v25, v0
	v_mov_b32_e32 v26, v0
	v_mov_b32_e32 v27, v0
	v_mov_b32_e32 v32, v0
	v_mov_b32_e32 v33, v0
	v_mov_b32_e32 v34, v0
	v_mov_b32_e32 v35, v0
	v_mov_b32_e32 v44, v0
	v_mov_b32_e32 v45, v0
	v_mov_b32_e32 v46, v0
	v_mov_b32_e32 v47, v0
	v_mov_b32_e32 v52, v0
	v_mov_b32_e32 v53, v0
	v_mov_b32_e32 v54, v0
	v_mov_b32_e32 v55, v0
	v_mov_b32_e32 v40, v0
	v_mov_b32_e32 v41, v0
	v_mov_b32_e32 v42, v0
	v_mov_b32_e32 v43, v0
	v_mov_b32_e32 v48, v0
	v_mov_b32_e32 v49, v0
	v_mov_b32_e32 v50, v0
	v_mov_b32_e32 v51, v0
	v_mov_b32_e32 v56, v0
	v_mov_b32_e32 v57, v0
	v_mov_b32_e32 v58, v0
	v_mov_b32_e32 v59, v0
	v_mov_b32_e32 v60, v0
	v_mov_b32_e32 v61, v0
	v_mov_b32_e32 v62, v0
	v_mov_b32_e32 v63, v0
	v_mov_b32_e32 v64, v0
	v_mov_b32_e32 v65, v0
	v_mov_b32_e32 v66, v0
	v_mov_b32_e32 v67, v0
	v_mov_b32_e32 v68, v0
	v_mov_b32_e32 v69, v0
	v_mov_b32_e32 v70, v0
	v_mov_b32_e32 v71, v0
	v_mov_b32_e32 v80, v0
	v_mov_b32_e32 v81, v0
	v_mov_b32_e32 v82, v0
	v_mov_b32_e32 v83, v0
	v_mov_b32_e32 v84, v0
	v_mov_b32_e32 v85, v0
	v_mov_b32_e32 v86, v0
	v_mov_b32_e32 v87, v0
	v_mov_b32_e32 v72, v0
	v_mov_b32_e32 v73, v0
	v_mov_b32_e32 v74, v0
	v_mov_b32_e32 v75, v0
	v_mov_b32_e32 v76, v0
	v_mov_b32_e32 v77, v0
	v_mov_b32_e32 v78, v0
	v_mov_b32_e32 v79, v0
	v_mov_b32_e32 v96, v0
	v_mov_b32_e32 v97, v0
	v_mov_b32_e32 v98, v0
	v_mov_b32_e32 v99, v0
	v_mov_b32_e32 v100, v0
	v_mov_b32_e32 v101, v0
	v_mov_b32_e32 v102, v0
	v_mov_b32_e32 v103, v0
	v_mov_b32_e32 v88, v0
	v_mov_b32_e32 v89, v0
	v_mov_b32_e32 v90, v0
	v_mov_b32_e32 v91, v0
	v_mov_b32_e32 v92, v0
	v_mov_b32_e32 v93, v0
	v_mov_b32_e32 v94, v0
	v_mov_b32_e32 v95, v0
	v_mov_b32_e32 v112, v0
	v_mov_b32_e32 v113, v0
	v_mov_b32_e32 v114, v0
	v_mov_b32_e32 v115, v0
	v_mov_b32_e32 v116, v0
	v_mov_b32_e32 v117, v0
	v_mov_b32_e32 v118, v0
	v_mov_b32_e32 v119, v0
	v_mov_b32_e32 v104, v0
	v_mov_b32_e32 v105, v0
	v_mov_b32_e32 v106, v0
	v_mov_b32_e32 v107, v0
	v_mov_b32_e32 v108, v0
	v_mov_b32_e32 v109, v0
	v_mov_b32_e32 v110, v0
	v_mov_b32_e32 v111, v0
	v_mov_b32_e32 v120, v0
	v_mov_b32_e32 v121, v0
	v_mov_b32_e32 v122, v0
	v_mov_b32_e32 v123, v0
	v_mov_b32_e32 v124, v0
	v_mov_b32_e32 v125, v0
	v_mov_b32_e32 v126, v0
	v_mov_b32_e32 v127, v0
	s_mov_b64 s[8:9], 0x180
	s_barrier
	ds_read_b128 v[178:181], v145
	ds_read_b128 v[182:185], v145 offset:1024
	ds_read_b128 v[186:189], v145 offset:2048
	ds_read_b128 v[190:193], v145 offset:3072
	v_lshl_add_u64 v[140:141], v[132:133], 0, v[136:137]
	v_readfirstlane_b32 s6, v177
	v_lshl_add_u64 v[142:143], v[140:141], 0, s[76:77]
	s_mov_b32 m0, s6
	v_readfirstlane_b32 s6, v176
	ds_read_b128 v[194:197], v144
	ds_read_b128 v[198:201], v144 offset:1024
	ds_read_b128 v[202:205], v144 offset:2048
	ds_read_b128 v[206:209], v144 offset:3072
	ds_read_b128 v[210:213], v144 offset:4096
	ds_read_b128 v[214:217], v144 offset:5120
	ds_read_b128 v[218:221], v144 offset:6144
	ds_read_b128 v[222:225], v144 offset:7168
	v_lshl_add_u64 v[142:143], v[140:141], 0, s[16:17]
	s_mov_b32 m0, s6
	s_nop 0
	s_waitcnt lgkmcnt(8)
	s_barrier
	s_waitcnt lgkmcnt(0)
	s_setprio 1
	s_waitcnt lgkmcnt(0)
	v_mfma_f32_16x16x32_bf16 v[124:127], v[178:181], v[194:197], v[124:127]
	v_mfma_f32_16x16x32_bf16 v[120:123], v[186:189], v[194:197], v[120:123]
	v_mfma_f32_16x16x32_bf16 v[116:119], v[178:181], v[202:205], v[116:119]
	v_mfma_f32_16x16x32_bf16 v[112:115], v[186:189], v[202:205], v[112:115]
	v_mfma_f32_16x16x32_bf16 v[100:103], v[178:181], v[210:213], v[100:103]
	v_mfma_f32_16x16x32_bf16 v[96:99], v[186:189], v[210:213], v[96:99]
	v_mfma_f32_16x16x32_bf16 v[84:87], v[178:181], v[218:221], v[84:87]
	v_mfma_f32_16x16x32_bf16 v[80:83], v[186:189], v[218:221], v[80:83]
	v_mfma_f32_16x16x32_bf16 v[124:127], v[182:185], v[198:201], v[124:127]
	v_mfma_f32_16x16x32_bf16 v[120:123], v[190:193], v[198:201], v[120:123]
	v_mfma_f32_16x16x32_bf16 v[116:119], v[182:185], v[206:209], v[116:119]
	v_mfma_f32_16x16x32_bf16 v[112:115], v[190:193], v[206:209], v[112:115]
	v_mfma_f32_16x16x32_bf16 v[100:103], v[182:185], v[214:217], v[100:103]
	v_mfma_f32_16x16x32_bf16 v[96:99], v[190:193], v[214:217], v[96:99]
	v_mfma_f32_16x16x32_bf16 v[84:87], v[182:185], v[222:225], v[84:87]
	v_mfma_f32_16x16x32_bf16 v[80:83], v[190:193], v[222:225], v[80:83]
	s_setprio 0
	s_barrier
	v_lshl_add_u64 v[142:143], v[130:131], 0, v[136:137]
	v_readfirstlane_b32 s6, v148
	v_lshl_add_u64 v[162:163], v[142:143], 0, s[86:87]
	s_mov_b32 m0, s6
	s_mov_b64 s[6:7], 0x20100
	ds_read_b128 v[226:229], v145 offset:16384
	ds_read_b128 v[230:233], v145 offset:17408
	ds_read_b128 v[234:237], v145 offset:18432
	ds_read_b128 v[238:241], v145 offset:19456
	global_load_lds_dwordx4 v[162:163], off
	v_lshl_add_u64 v[162:163], v[142:143], 0, s[6:7]
	v_readfirstlane_b32 s6, v149
	s_mov_b32 m0, s6
	s_nop 0
	global_load_lds_dwordx4 v[162:163], off
	s_barrier
	s_waitcnt lgkmcnt(0)
	s_setprio 1
	s_waitcnt lgkmcnt(0)
	v_mfma_f32_16x16x32_bf16 v[108:111], v[226:229], v[194:197], v[108:111]
	v_mfma_f32_16x16x32_bf16 v[104:107], v[234:237], v[194:197], v[104:107]
	v_mfma_f32_16x16x32_bf16 v[92:95], v[226:229], v[202:205], v[92:95]
	v_mfma_f32_16x16x32_bf16 v[88:91], v[234:237], v[202:205], v[88:91]
	v_mfma_f32_16x16x32_bf16 v[76:79], v[226:229], v[210:213], v[76:79]
	v_mfma_f32_16x16x32_bf16 v[72:75], v[234:237], v[210:213], v[72:75]
	v_mfma_f32_16x16x32_bf16 v[68:71], v[226:229], v[218:221], v[68:71]
	v_mfma_f32_16x16x32_bf16 v[64:67], v[234:237], v[218:221], v[64:67]
	v_mfma_f32_16x16x32_bf16 v[108:111], v[230:233], v[198:201], v[108:111]
	v_mfma_f32_16x16x32_bf16 v[104:107], v[238:241], v[198:201], v[104:107]
	v_mfma_f32_16x16x32_bf16 v[92:95], v[230:233], v[206:209], v[92:95]
	v_mfma_f32_16x16x32_bf16 v[88:91], v[238:241], v[206:209], v[88:91]
	v_mfma_f32_16x16x32_bf16 v[76:79], v[230:233], v[214:217], v[76:79]
	v_mfma_f32_16x16x32_bf16 v[72:75], v[238:241], v[214:217], v[72:75]
	v_mfma_f32_16x16x32_bf16 v[68:71], v[230:233], v[222:225], v[68:71]
	v_mfma_f32_16x16x32_bf16 v[64:67], v[238:241], v[222:225], v[64:67]
	s_setprio 0
	v_readfirstlane_b32 s6, v146
	v_lshl_add_u64 v[162:163], v[140:141], 0, s[88:89]
	s_mov_b32 m0, s6
	v_readfirstlane_b32 s6, v150
	s_barrier
	ds_read_b128 v[194:197], v144 offset:16384
	ds_read_b128 v[198:201], v144 offset:17408
	ds_read_b128 v[202:205], v144 offset:18432
	ds_read_b128 v[206:209], v144 offset:19456
	ds_read_b128 v[210:213], v144 offset:20480
	ds_read_b128 v[214:217], v144 offset:21504
	ds_read_b128 v[218:221], v144 offset:22528
	ds_read_b128 v[222:225], v144 offset:23552
	global_load_lds_dwordx4 v[162:163], off
	v_lshl_add_u64 v[162:163], v[140:141], 0, s[90:91]
	s_mov_b32 m0, s6
	s_nop 0
	global_load_lds_dwordx4 v[162:163], off
	s_barrier
	s_waitcnt lgkmcnt(0)
	s_setprio 1
	s_waitcnt lgkmcnt(0)
	v_mfma_f32_16x16x32_bf16 v[60:63], v[178:181], v[194:197], v[60:63]
	v_mfma_f32_16x16x32_bf16 v[56:59], v[186:189], v[194:197], v[56:59]
	v_mfma_f32_16x16x32_bf16 v[52:55], v[178:181], v[202:205], v[52:55]
	v_mfma_f32_16x16x32_bf16 v[44:47], v[186:189], v[202:205], v[44:47]
	v_mfma_f32_16x16x32_bf16 v[36:39], v[178:181], v[210:213], v[36:39]
	v_mfma_f32_16x16x32_bf16 v[28:31], v[186:189], v[210:213], v[28:31]
	v_mfma_f32_16x16x32_bf16 v[20:23], v[178:181], v[218:221], v[20:23]
	v_mfma_f32_16x16x32_bf16 v[12:15], v[186:189], v[218:221], v[12:15]
	v_mfma_f32_16x16x32_bf16 v[60:63], v[182:185], v[198:201], v[60:63]
	v_mfma_f32_16x16x32_bf16 v[56:59], v[190:193], v[198:201], v[56:59]
	v_mfma_f32_16x16x32_bf16 v[52:55], v[182:185], v[206:209], v[52:55]
	v_mfma_f32_16x16x32_bf16 v[44:47], v[190:193], v[206:209], v[44:47]
	v_mfma_f32_16x16x32_bf16 v[36:39], v[182:185], v[214:217], v[36:39]
	v_mfma_f32_16x16x32_bf16 v[28:31], v[190:193], v[214:217], v[28:31]
	v_mfma_f32_16x16x32_bf16 v[20:23], v[182:185], v[222:225], v[20:23]
	v_mfma_f32_16x16x32_bf16 v[12:15], v[190:193], v[222:225], v[12:15]
	s_setprio 0
	s_barrier
	s_mov_b64 s[6:7], 0x40100
	v_lshl_add_u64 v[162:163], v[142:143], 0, s[6:7]
	v_readfirstlane_b32 s6, v151
	s_mov_b32 m0, s6
	s_mov_b64 s[6:7], 0x60100
	global_load_lds_dwordx4 v[162:163], off
	v_lshl_add_u64 v[162:163], v[142:143], 0, s[6:7]
	v_readfirstlane_b32 s6, v152
	s_mov_b32 m0, s6
	s_nop 0
	global_load_lds_dwordx4 v[162:163], off
	s_waitcnt vmcnt(14)
	s_barrier
	s_setprio 1
	v_mfma_f32_16x16x32_bf16 v[48:51], v[226:229], v[194:197], v[48:51]
	v_mfma_f32_16x16x32_bf16 v[40:43], v[234:237], v[194:197], v[40:43]
	v_mfma_f32_16x16x32_bf16 v[32:35], v[226:229], v[202:205], v[32:35]
	v_mfma_f32_16x16x32_bf16 v[24:27], v[234:237], v[202:205], v[24:27]
	v_mfma_f32_16x16x32_bf16 v[16:19], v[226:229], v[210:213], v[16:19]
	v_mfma_f32_16x16x32_bf16 v[8:11], v[234:237], v[210:213], v[8:11]
	v_mfma_f32_16x16x32_bf16 v[4:7], v[226:229], v[218:221], v[4:7]
	v_mfma_f32_16x16x32_bf16 v[0:3], v[234:237], v[218:221], v[0:3]
	v_mfma_f32_16x16x32_bf16 v[48:51], v[230:233], v[198:201], v[48:51]
	v_mfma_f32_16x16x32_bf16 v[40:43], v[238:241], v[198:201], v[40:43]
	v_mfma_f32_16x16x32_bf16 v[32:35], v[230:233], v[206:209], v[32:35]
	v_mfma_f32_16x16x32_bf16 v[24:27], v[238:241], v[206:209], v[24:27]
	v_mfma_f32_16x16x32_bf16 v[16:19], v[230:233], v[214:217], v[16:19]
	v_mfma_f32_16x16x32_bf16 v[8:11], v[238:241], v[214:217], v[8:11]
	v_mfma_f32_16x16x32_bf16 v[4:7], v[230:233], v[222:225], v[4:7]
	v_mfma_f32_16x16x32_bf16 v[0:3], v[238:241], v[222:225], v[0:3]
	s_setprio 0
	s_barrier
	ds_read_b128 v[178:181], v139
	ds_read_b128 v[182:185], v139 offset:1024
	ds_read_b128 v[186:189], v139 offset:2048
	ds_read_b128 v[190:193], v139 offset:3072
	v_readfirstlane_b32 s6, v153
	v_lshl_add_u64 v[162:163], v[140:141], 0, s[94:95]
	s_mov_b32 m0, s6
	v_readfirstlane_b32 s6, v170
	ds_read_b128 v[194:197], v135
	ds_read_b128 v[198:201], v135 offset:1024
	ds_read_b128 v[202:205], v135 offset:2048
	ds_read_b128 v[206:209], v135 offset:3072
	ds_read_b128 v[210:213], v135 offset:4096
	ds_read_b128 v[214:217], v135 offset:5120
	ds_read_b128 v[218:221], v135 offset:6144
	ds_read_b128 v[222:225], v135 offset:7168
	global_load_lds_dwordx4 v[162:163], off
	v_lshl_add_u64 v[162:163], v[140:141], 0, s[78:79]
	s_mov_b32 m0, s6
	s_nop 0
	global_load_lds_dwordx4 v[162:163], off
	s_waitcnt lgkmcnt(8)
	s_barrier
	s_waitcnt lgkmcnt(0)
	s_setprio 1
	s_waitcnt lgkmcnt(0)
	v_mfma_f32_16x16x32_bf16 v[124:127], v[178:181], v[194:197], v[124:127]
	v_mfma_f32_16x16x32_bf16 v[120:123], v[186:189], v[194:197], v[120:123]
	v_mfma_f32_16x16x32_bf16 v[116:119], v[178:181], v[202:205], v[116:119]
	v_mfma_f32_16x16x32_bf16 v[112:115], v[186:189], v[202:205], v[112:115]
	v_mfma_f32_16x16x32_bf16 v[100:103], v[178:181], v[210:213], v[100:103]
	v_mfma_f32_16x16x32_bf16 v[96:99], v[186:189], v[210:213], v[96:99]
	v_mfma_f32_16x16x32_bf16 v[84:87], v[178:181], v[218:221], v[84:87]
	v_mfma_f32_16x16x32_bf16 v[80:83], v[186:189], v[218:221], v[80:83]
	v_mfma_f32_16x16x32_bf16 v[124:127], v[182:185], v[198:201], v[124:127]
	v_mfma_f32_16x16x32_bf16 v[120:123], v[190:193], v[198:201], v[120:123]
	v_mfma_f32_16x16x32_bf16 v[116:119], v[182:185], v[206:209], v[116:119]
	v_mfma_f32_16x16x32_bf16 v[112:115], v[190:193], v[206:209], v[112:115]
	v_mfma_f32_16x16x32_bf16 v[100:103], v[182:185], v[214:217], v[100:103]
	v_mfma_f32_16x16x32_bf16 v[96:99], v[190:193], v[214:217], v[96:99]
	v_mfma_f32_16x16x32_bf16 v[84:87], v[182:185], v[222:225], v[84:87]
	v_mfma_f32_16x16x32_bf16 v[80:83], v[190:193], v[222:225], v[80:83]
	s_setprio 0
	s_barrier
	v_readfirstlane_b32 s6, v171
	v_lshl_add_u64 v[162:163], v[142:143], 0, s[8:9]
	s_mov_b32 m0, s6
	s_mov_b64 s[6:7], 0x20180
	ds_read_b128 v[226:229], v139 offset:16384
	ds_read_b128 v[230:233], v139 offset:17408
	ds_read_b128 v[234:237], v139 offset:18432
	ds_read_b128 v[238:241], v139 offset:19456
	global_load_lds_dwordx4 v[162:163], off
	v_lshl_add_u64 v[162:163], v[142:143], 0, s[6:7]
	v_readfirstlane_b32 s6, v172
	s_mov_b32 m0, s6
	s_nop 0
	global_load_lds_dwordx4 v[162:163], off
	s_barrier
	s_waitcnt lgkmcnt(0)
	s_setprio 1
	s_waitcnt lgkmcnt(0)
	v_mfma_f32_16x16x32_bf16 v[108:111], v[226:229], v[194:197], v[108:111]
	v_mfma_f32_16x16x32_bf16 v[104:107], v[234:237], v[194:197], v[104:107]
	v_mfma_f32_16x16x32_bf16 v[92:95], v[226:229], v[202:205], v[92:95]
	v_mfma_f32_16x16x32_bf16 v[88:91], v[234:237], v[202:205], v[88:91]
	v_mfma_f32_16x16x32_bf16 v[76:79], v[226:229], v[210:213], v[76:79]
	v_mfma_f32_16x16x32_bf16 v[72:75], v[234:237], v[210:213], v[72:75]
	v_mfma_f32_16x16x32_bf16 v[68:71], v[226:229], v[218:221], v[68:71]
	v_mfma_f32_16x16x32_bf16 v[64:67], v[234:237], v[218:221], v[64:67]
	v_mfma_f32_16x16x32_bf16 v[108:111], v[230:233], v[198:201], v[108:111]
	v_mfma_f32_16x16x32_bf16 v[104:107], v[238:241], v[198:201], v[104:107]
	v_mfma_f32_16x16x32_bf16 v[92:95], v[230:233], v[206:209], v[92:95]
	v_mfma_f32_16x16x32_bf16 v[88:91], v[238:241], v[206:209], v[88:91]
	v_mfma_f32_16x16x32_bf16 v[76:79], v[230:233], v[214:217], v[76:79]
	v_mfma_f32_16x16x32_bf16 v[72:75], v[238:241], v[214:217], v[72:75]
	v_mfma_f32_16x16x32_bf16 v[68:71], v[230:233], v[222:225], v[68:71]
	v_mfma_f32_16x16x32_bf16 v[64:67], v[238:241], v[222:225], v[64:67]
	s_setprio 0
	v_readfirstlane_b32 s6, v147
	v_lshl_add_u64 v[162:163], v[140:141], 0, s[24:25]
	s_mov_b32 m0, s6
	v_readfirstlane_b32 s6, v173
	s_barrier
	ds_read_b128 v[194:197], v135 offset:16384
	ds_read_b128 v[198:201], v135 offset:17408
	ds_read_b128 v[202:205], v135 offset:18432
	ds_read_b128 v[206:209], v135 offset:19456
	ds_read_b128 v[210:213], v135 offset:20480
	ds_read_b128 v[214:217], v135 offset:21504
	ds_read_b128 v[218:221], v135 offset:22528
	ds_read_b128 v[222:225], v135 offset:23552
	global_load_lds_dwordx4 v[162:163], off
	v_lshl_add_u64 v[140:141], v[140:141], 0, s[28:29]
	s_mov_b32 m0, s6
	s_nop 0
	global_load_lds_dwordx4 v[140:141], off
	s_barrier
	s_waitcnt lgkmcnt(0)
	s_setprio 1
	s_waitcnt lgkmcnt(0)
	v_mfma_f32_16x16x32_bf16 v[60:63], v[178:181], v[194:197], v[60:63]
	v_mfma_f32_16x16x32_bf16 v[56:59], v[186:189], v[194:197], v[56:59]
	v_mfma_f32_16x16x32_bf16 v[52:55], v[178:181], v[202:205], v[52:55]
	v_mfma_f32_16x16x32_bf16 v[44:47], v[186:189], v[202:205], v[44:47]
	v_mfma_f32_16x16x32_bf16 v[36:39], v[178:181], v[210:213], v[36:39]
	v_mfma_f32_16x16x32_bf16 v[28:31], v[186:189], v[210:213], v[28:31]
	v_mfma_f32_16x16x32_bf16 v[20:23], v[178:181], v[218:221], v[20:23]
	v_mfma_f32_16x16x32_bf16 v[12:15], v[186:189], v[218:221], v[12:15]
	v_mfma_f32_16x16x32_bf16 v[60:63], v[182:185], v[198:201], v[60:63]
	v_mfma_f32_16x16x32_bf16 v[56:59], v[190:193], v[198:201], v[56:59]
	v_mfma_f32_16x16x32_bf16 v[52:55], v[182:185], v[206:209], v[52:55]
	v_mfma_f32_16x16x32_bf16 v[44:47], v[190:193], v[206:209], v[44:47]
	v_mfma_f32_16x16x32_bf16 v[36:39], v[182:185], v[214:217], v[36:39]
	v_mfma_f32_16x16x32_bf16 v[28:31], v[190:193], v[214:217], v[28:31]
	v_mfma_f32_16x16x32_bf16 v[20:23], v[182:185], v[222:225], v[20:23]
	v_mfma_f32_16x16x32_bf16 v[12:15], v[190:193], v[222:225], v[12:15]
	s_setprio 0
	s_barrier
	s_mov_b64 s[6:7], 0x40180
	v_lshl_add_u64 v[140:141], v[142:143], 0, s[6:7]
	v_readfirstlane_b32 s6, v174
	s_mov_b32 m0, s6
	s_mov_b64 s[6:7], 0x60180
	global_load_lds_dwordx4 v[140:141], off
	v_lshl_add_u64 v[140:141], v[142:143], 0, s[6:7]
	v_readfirstlane_b32 s6, v175
	s_mov_b32 m0, s6
	s_nop 0
	global_load_lds_dwordx4 v[140:141], off
	s_waitcnt vmcnt(6)
	s_barrier
	s_setprio 1
	v_mfma_f32_16x16x32_bf16 v[48:51], v[226:229], v[194:197], v[48:51]
	v_mfma_f32_16x16x32_bf16 v[40:43], v[234:237], v[194:197], v[40:43]
	v_mfma_f32_16x16x32_bf16 v[32:35], v[226:229], v[202:205], v[32:35]
	v_mfma_f32_16x16x32_bf16 v[24:27], v[234:237], v[202:205], v[24:27]
	v_mfma_f32_16x16x32_bf16 v[16:19], v[226:229], v[210:213], v[16:19]
	v_mfma_f32_16x16x32_bf16 v[8:11], v[234:237], v[210:213], v[8:11]
	v_mfma_f32_16x16x32_bf16 v[4:7], v[226:229], v[218:221], v[4:7]
	v_mfma_f32_16x16x32_bf16 v[0:3], v[234:237], v[218:221], v[0:3]
	v_mfma_f32_16x16x32_bf16 v[48:51], v[230:233], v[198:201], v[48:51]
	v_mfma_f32_16x16x32_bf16 v[40:43], v[238:241], v[198:201], v[40:43]
	v_mfma_f32_16x16x32_bf16 v[32:35], v[230:233], v[206:209], v[32:35]
	v_mfma_f32_16x16x32_bf16 v[24:27], v[238:241], v[206:209], v[24:27]
	v_mfma_f32_16x16x32_bf16 v[16:19], v[230:233], v[214:217], v[16:19]
	v_mfma_f32_16x16x32_bf16 v[8:11], v[238:241], v[214:217], v[8:11]
	v_mfma_f32_16x16x32_bf16 v[4:7], v[230:233], v[222:225], v[4:7]
	v_mfma_f32_16x16x32_bf16 v[0:3], v[238:241], v[222:225], v[0:3]
	s_setprio 0
	s_add_i32 s5, s5, 2
	v_lshl_add_u64 v[130:131], v[130:131], 0, s[86:87]
	s_cmp_gt_u32 s5, 11
	v_lshl_add_u64 v[132:133], v[132:133], 0, s[86:87]
	s_barrier
	s_branch .LBB0_114

.LBB0_221:
	s_add_i32 s8, s8, s74
	s_add_i32 s11, s11, s20
	s_cmpk_lt_i32 s8, 0x880
	s_cbranch_scc0 .LBB0_242
	s_branch .LP2_in

.LBB0_228:
	s_or_b64 exec, exec, s[0:1]
	s_add_i32 s36, s8, s74
	s_cmpk_gt_i32 s36, 0x87f
	s_cbranch_scc1 .Lt2_skip_in
	s_lshl_b32 s37, s36, 3
	s_and_b32 s37, s37, 56
	s_bfe_u32 s43, s36, 0x30003
	s_or_b32 s37, s37, s43
	s_lshl_b32 s37, s37, 19
	v_readlane_b32 s38, v253, 47
	v_readlane_b32 s39, v253, 48
	s_add_u32 s38, s38, s37
	s_addc_u32 s39, s39, 0
	s_ashr_i32 s43, s36, 6
	s_lshl_b32 s43, s43, 19
	s_add_u32 s40, s9, s43
	s_addc_u32 s41, s10, 0
	v_lshrrev_b32_e32 v243, 7, v154
	v_bfe_u32 v244, v154, 2, 4
	v_lshl_add_u32 v243, v243, 4, v244
	v_bfe_u32 v244, v154, 5, 1
	v_lshlrev_b32_e32 v244, 1, v244
	v_and_b32_e32 v245, 3, v154
	v_xor_b32_e32 v244, v244, v245
	v_lshlrev_b32_e32 v244, 4, v244
	v_bfe_u32 v245, v154, 6, 1
	v_lshl_or_b32 v244, v245, 6, v244
	v_lshl_or_b32 v242, v243, 11, v244
	v_lshrrev_b32_e32 v245, 6, v154
	v_lshlrev_b32_e32 v245, 10, v245
	s_nop 0
	v_readfirstlane_b32 s42, v245
	s_add_u32 m0, s42, 0x8000
	s_nop 0
	global_load_lds_dwordx4 v242, s[40:41]
	s_add_u32 m0, s42, 0xa000
	s_add_u32 s40, s40, 0x20000
	s_addc_u32 s41, s41, 0
	global_load_lds_dwordx4 v242, s[40:41]
	s_add_u32 m0, s42, 0x0
	s_nop 0
	global_load_lds_dwordx4 v242, s[38:39]
	s_add_u32 m0, s42, 0x2000
	s_add_u32 s38, s38, 0x20000
	s_addc_u32 s39, s39, 0
	global_load_lds_dwordx4 v242, s[38:39]
	s_add_u32 m0, s42, 0xc000
	s_add_u32 s40, s40, 0x20000
	s_addc_u32 s41, s41, 0
	global_load_lds_dwordx4 v242, s[40:41]
	s_add_u32 m0, s42, 0xe000
	s_add_u32 s40, s40, 0x20000
	s_addc_u32 s41, s41, 0
	global_load_lds_dwordx4 v242, s[40:41]
	s_add_u32 m0, s42, 0x4000
	s_add_u32 s38, s38, 0x20000
	s_addc_u32 s39, s39, 0
	global_load_lds_dwordx4 v242, s[38:39]
	s_add_u32 m0, s42, 0x6000
	s_add_u32 s38, s38, 0x20000
	s_addc_u32 s39, s39, 0
	global_load_lds_dwordx4 v242, s[38:39]
	s_add_u32 m0, s42, 0x18000
	s_sub_u32 s40, s40, 0x5ff80
	s_subb_u32 s41, s41, 0
	global_load_lds_dwordx4 v242, s[40:41]
	s_add_u32 m0, s42, 0x1a000
	s_add_u32 s40, s40, 0x20000
	s_addc_u32 s41, s41, 0
	global_load_lds_dwordx4 v242, s[40:41]
	s_add_u32 m0, s42, 0x10000
	s_sub_u32 s38, s38, 0x5ff80
	s_subb_u32 s39, s39, 0
	global_load_lds_dwordx4 v242, s[38:39]
	s_add_u32 m0, s42, 0x12000
	s_add_u32 s38, s38, 0x20000
	s_addc_u32 s39, s39, 0
	global_load_lds_dwordx4 v242, s[38:39]
	s_add_u32 m0, s42, 0x1c000
	s_add_u32 s40, s40, 0x20000
	s_addc_u32 s41, s41, 0
	global_load_lds_dwordx4 v242, s[40:41]
	s_add_u32 m0, s42, 0x1e000
	s_add_u32 s40, s40, 0x20000
	s_addc_u32 s41, s41, 0
	global_load_lds_dwordx4 v242, s[40:41]
	s_add_u32 m0, s42, 0x14000
	s_add_u32 s38, s38, 0x20000
	s_addc_u32 s39, s39, 0
	global_load_lds_dwordx4 v242, s[38:39]
	s_add_u32 m0, s42, 0x16000
	s_add_u32 s38, s38, 0x20000
	s_addc_u32 s39, s39, 0
	global_load_lds_dwordx4 v242, s[38:39]
.Lt2_skip_in:
	v_mov_b32_e32 v131, v154
	s_cmp_gt_i32 s4, 8
	v_ashrrev_i32_e32 v130, 8, v131
	v_bfe_u32 v129, v131, 6, 2
	v_and_b32_e32 v128, 15, v131
	v_bfe_u32 v131, v131, 4, 2
	s_mov_b64 s[0:1], -1
	s_cbranch_scc0 .LBB0_240
	s_cmp_gt_u32 s4, 20
	s_cbranch_scc0 .LBB0_237
	s_cmp_gt_u32 s4, 32
	s_cbranch_scc0 .LBB0_234
	v_cmp_eq_u32_e32 vcc, 0, v129
	v_cmp_gt_u32_e64 s[0:1], 2, v131
	s_and_b64 s[6:7], vcc, s[0:1]
	s_and_saveexec_b64 s[0:1], s[6:7]
	s_cbranch_execz .LBB0_233
	v_lshlrev_b32_e32 v132, 6, v130
	s_lshl_b32 s6, s12, 8
	s_mov_b32 s7, s52
	v_ashrrev_i32_e32 v133, 31, v132
	v_lshl_add_u64 v[132:133], s[6:7], 0, v[132:133]
	v_or_b32_e32 v132, v132, v128
	v_readlane_b32 s6, v253, 61
	v_lshlrev_b64 v[132:133], 6, v[132:133]
	v_readlane_b32 s7, v253, 62
	v_lshlrev_b32_e32 v136, 5, v131
	s_nop 0
	v_lshl_add_u64 v[134:135], s[6:7], 0, v[132:133]
	v_readlane_b32 s6, v253, 63
	v_readlane_b32 s7, v254, 0
	v_lshl_add_u64 v[134:135], v[134:135], 0, v[136:137]
	global_store_dwordx4 v[134:135], v[120:123], off
	global_store_dwordx4 v[134:135], v[124:127], off offset:16
	v_lshl_add_u64 v[140:141], s[6:7], 0, v[132:133]
	v_readlane_b32 s6, v254, 1
	v_lshl_add_u64 v[140:141], v[140:141], 0, v[136:137]
	v_readlane_b32 s7, v254, 2
	global_store_dwordx4 v[140:141], v[112:115], off
	global_store_dwordx4 v[140:141], v[116:119], off offset:16
	v_lshl_add_u64 v[140:141], s[6:7], 0, v[132:133]
	v_readlane_b32 s6, v254, 3
	v_readlane_b32 s7, v254, 4
	v_lshl_add_u64 v[140:141], v[140:141], 0, v[136:137]
	global_store_dwordx4 v[140:141], v[96:99], off
	global_store_dwordx4 v[140:141], v[100:103], off offset:16
	v_lshl_add_u64 v[132:133], s[6:7], 0, v[132:133]
	v_lshl_add_u64 v[132:133], v[132:133], 0, v[136:137]
	s_mov_b64 s[6:7], 0x2000
	v_add_co_u32_e32 v140, vcc, 0x2000, v134
	global_store_dwordx4 v[132:133], v[88:91], off
	global_store_dwordx4 v[132:133], v[92:95], off offset:16
	v_lshl_add_u64 v[132:133], v[134:135], 0, s[6:7]
	v_addc_co_u32_e32 v141, vcc, 0, v135, vcc
	s_mov_b64 s[6:7], 0x2400
	global_store_dwordx4 v[140:141], v[104:107], off
	global_store_dwordx4 v[132:133], v[108:111], off offset:16
	v_lshl_add_u64 v[132:133], v[134:135], 0, s[6:7]
	s_mov_b64 s[6:7], 0x2800
	global_store_dwordx4 v[140:141], v[80:83], off offset:1024
	global_store_dwordx4 v[132:133], v[84:87], off offset:16
	v_lshl_add_u64 v[132:133], v[134:135], 0, s[6:7]
	s_mov_b64 s[6:7], 0x2c00
	global_store_dwordx4 v[140:141], v[72:75], off offset:2048
	global_store_dwordx4 v[132:133], v[76:79], off offset:16
	v_lshl_add_u64 v[132:133], v[134:135], 0, s[6:7]
	global_store_dwordx4 v[140:141], v[64:67], off offset:3072
	global_store_dwordx4 v[132:133], v[68:71], off offset:16

.LP2_in:
	s_lshl_b32 s0, s8, 3
	s_and_b32 s0, s0, 56
	s_bfe_u32 s1, s8, 0x30003
	v_mov_b32_e32 v134, v154
	s_or_b32 s12, s0, s1
	s_ashr_i32 s4, s8, 6
	v_ashrrev_i32_e32 v5, 6, v134
	v_lshrrev_b32_e32 v1, 4, v134
	v_ashrrev_i32_e32 v4, 3, v134
	v_lshrrev_b32_e32 v0, 2, v134
	v_and_b32_e32 v3, 3, v134
	s_lshl_b32 s0, s12, 19
	v_readlane_b32 s6, v253, 47
	v_bfi_b32 v0, -16, v4, v0
	v_lshlrev_b32_e32 v2, 5, v5
	v_bitop3_b32 v1, v1, v3, 2 bitop3:0x6c
	v_readlane_b32 s7, v253, 48
	s_add_u32 s6, s6, s0
	v_and_b32_e32 v2, 32, v2
	v_lshlrev_b32_e32 v3, 3, v1
	v_ashrrev_i32_e32 v1, 31, v0
	s_addc_u32 s7, s7, 0
	v_or_b32_e32 v11, v3, v2
	v_lshlrev_b64 v[0:1], 11, v[0:1]
	v_and_b32_e32 v9, 15, v134
	v_lshl_add_u64 v[6:7], s[6:7], 0, v[0:1]
	v_lshlrev_b32_e32 v136, 1, v11
	v_lshl_add_u64 v[128:129], v[6:7], 0, v[136:137]
	v_lshlrev_b32_e32 v6, 6, v9
	v_lshlrev_b32_e32 v9, 2, v134
	v_ashrrev_i32_e32 v8, 8, v134
	v_and_b32_e32 v10, 48, v134
	v_and_b32_e32 v9, 32, v9
	s_ashr_i32 s5, s4, 31
	v_or_b32_e32 v7, v6, v10
	v_bitop3_b32 v6, v6, v9, v10 bitop3:0x36
	v_lshlrev_b32_e32 v10, 13, v8
	v_lshlrev_b32_e32 v5, 12, v5
	s_lshl_b64 s[0:1], s[4:5], 19
	v_lshlrev_b32_e32 v146, 4, v134
	v_bitop3_b32 v144, v7, v10, v9 bitop3:0xde
	v_and_or_b32 v5, v5, s75, v6
	s_add_u32 s14, s9, s0
	v_add_u32_e32 v147, 0x10000, v146
	v_add_u32_e32 v135, 0x10000, v144
	v_or_b32_e32 v145, 0x8000, v5
	v_or_b32_e32 v139, 0x18000, v5
	s_addc_u32 s15, s10, s1
	v_lshl_add_u64 v[0:1], s[14:15], 0, v[0:1]
	v_add_u32_e32 v148, 0x8000, v146
	v_add_u32_e32 v149, 0xa000, v146
	v_readfirstlane_b32 s5, v148
	v_lshl_add_u64 v[0:1], v[0:1], 0, v[136:137]
	s_mov_b32 m0, s5
	s_mov_b64 s[6:7], 0x20000
	v_readfirstlane_b32 s5, v149
	v_lshl_add_u64 v[6:7], v[0:1], 0, s[6:7]
	s_mov_b32 m0, s5
	v_readfirstlane_b32 s5, v146
	v_add_u32_e32 v150, 0x2000, v146
	s_mov_b32 m0, s5
	v_readfirstlane_b32 s5, v150
	v_add_u32_e32 v151, 0xc000, v146
	v_lshl_add_u64 v[6:7], v[128:129], 0, s[6:7]
	s_mov_b32 m0, s5
	s_mov_b64 s[6:7], 0x40000
	v_readfirstlane_b32 s5, v151
	v_add_u32_e32 v152, 0xe000, v146
	v_lshl_add_u64 v[6:7], v[0:1], 0, s[6:7]
	s_mov_b32 m0, s5
	s_mov_b64 s[14:15], 0x60000
	v_readfirstlane_b32 s5, v152
	v_add_u32_e32 v153, 0x4000, v146
	v_lshl_add_u64 v[6:7], v[0:1], 0, s[14:15]
	s_mov_b32 m0, s5
	v_readfirstlane_b32 s5, v153
	v_add_u32_e32 v170, 0x6000, v146
	v_lshl_add_u64 v[6:7], v[128:129], 0, s[6:7]
	s_mov_b32 m0, s5
	v_readfirstlane_b32 s5, v170
	v_lshl_add_u64 v[6:7], v[128:129], 0, s[14:15]
	s_mov_b32 m0, s5
	v_cmp_eq_u32_e32 vcc, 1, v8
	s_and_saveexec_b64 s[6:7], vcc
	s_cbranch_execz .LP2_in_224
	s_barrier
.LP2_in_224:
	s_or_b64 exec, exec, s[6:7]
	s_lshr_b32 s5, s8, 3
	s_and_b32 s5, s5, 7
	s_lshl_b32 s6, s11, 19
	s_lshl_b32 s5, s5, 19
	s_and_b32 s6, s6, 0x1c00000
	v_add_u32_e32 v171, 0x8000, v147
	s_or_b32 s5, s6, s5
	s_mov_b64 s[26:27], 0x80
	v_readfirstlane_b32 s6, v171
	v_add_u32_e32 v172, 0xa000, v147
	v_and_b32_e32 v6, -16, v4
	v_lshl_add_u64 v[4:5], v[0:1], 0, s[26:27]
	s_mov_b32 m0, s6
	s_mov_b64 s[36:37], 0x20080
	v_readfirstlane_b32 s6, v172
	s_waitcnt vmcnt(28)
	s_barrier
	v_lshl_add_u64 v[4:5], v[0:1], 0, s[36:37]
	s_mov_b32 m0, s6
	v_readfirstlane_b32 s6, v147
	v_add_u32_e32 v173, 0x2000, v147
	v_lshl_add_u64 v[4:5], v[128:129], 0, s[26:27]
	s_mov_b32 m0, s6
	v_readfirstlane_b32 s6, v173
	v_lshl_add_u64 v[4:5], v[128:129], 0, s[36:37]
	s_mov_b32 m0, s6
	s_mov_b64 s[6:7], 0x40080
	v_add_u32_e32 v174, 0xc000, v147
	v_lshl_add_u64 v[4:5], v[0:1], 0, s[6:7]
	v_readfirstlane_b32 s6, v174
	s_mov_b32 m0, s6
	s_mov_b64 s[6:7], 0x60080
	v_add_u32_e32 v175, 0xe000, v147
	v_lshl_add_u64 v[0:1], v[0:1], 0, s[6:7]
	v_readfirstlane_b32 s6, v175
	s_mov_b32 m0, s6
	v_bfe_u32 v7, v134, 2, 4
	v_add_u32_e32 v0, v6, v7
	v_ashrrev_i32_e32 v1, 31, v0
	s_add_u32 s0, s21, s0
	v_lshlrev_b64 v[0:1], 11, v[0:1]
	s_addc_u32 s1, s22, s1
	v_lshl_add_u64 v[130:131], s[0:1], 0, v[0:1]
	s_add_u32 s0, s72, s5
	s_waitcnt vmcnt(24)
	s_addc_u32 s1, s73, 0
	v_lshl_add_u64 v[132:133], s[0:1], 0, v[0:1]
	v_mov_b32_e32 v0, 0
	s_mov_b64 s[14:15], 0x80
	v_add_lshl_u32 v136, v2, v3, 1
	s_mov_b32 s0, -2
	v_mov_b32_e32 v1, v0
	v_mov_b32_e32 v2, v0
	v_mov_b32_e32 v3, v0
	v_mov_b32_e32 v4, v0
	v_mov_b32_e32 v5, v0
	v_mov_b32_e32 v6, v0
	v_mov_b32_e32 v7, v0
	v_mov_b32_e32 v12, v0
	v_mov_b32_e32 v13, v0
	v_mov_b32_e32 v14, v0
	v_mov_b32_e32 v15, v0
	v_mov_b32_e32 v20, v0
	v_mov_b32_e32 v21, v0
	v_mov_b32_e32 v22, v0
	v_mov_b32_e32 v23, v0
	v_mov_b32_e32 v8, v0
	v_mov_b32_e32 v9, v0
	v_mov_b32_e32 v10, v0
	v_mov_b32_e32 v11, v0
	v_mov_b32_e32 v16, v0
	v_mov_b32_e32 v17, v0
	v_mov_b32_e32 v18, v0
	v_mov_b32_e32 v19, v0
	v_mov_b32_e32 v28, v0
	v_mov_b32_e32 v29, v0
	v_mov_b32_e32 v30, v0
	v_mov_b32_e32 v31, v0
	v_mov_b32_e32 v36, v0
	v_mov_b32_e32 v37, v0
	v_mov_b32_e32 v38, v0
	v_mov_b32_e32 v39, v0
	v_mov_b32_e32 v24, v0
	v_mov_b32_e32 v25, v0
	v_mov_b32_e32 v26, v0
	v_mov_b32_e32 v27, v0
	v_mov_b32_e32 v32, v0
	v_mov_b32_e32 v33, v0
	v_mov_b32_e32 v34, v0
	v_mov_b32_e32 v35, v0
	v_mov_b32_e32 v44, v0
	v_mov_b32_e32 v45, v0
	v_mov_b32_e32 v46, v0
	v_mov_b32_e32 v47, v0
	v_mov_b32_e32 v52, v0
	v_mov_b32_e32 v53, v0
	v_mov_b32_e32 v54, v0
	v_mov_b32_e32 v55, v0
	v_mov_b32_e32 v40, v0
	v_mov_b32_e32 v41, v0
	v_mov_b32_e32 v42, v0
	v_mov_b32_e32 v43, v0
	v_mov_b32_e32 v48, v0
	v_mov_b32_e32 v49, v0
	v_mov_b32_e32 v50, v0
	v_mov_b32_e32 v51, v0
	v_mov_b32_e32 v56, v0
	v_mov_b32_e32 v57, v0
	v_mov_b32_e32 v58, v0
	v_mov_b32_e32 v59, v0
	v_mov_b32_e32 v60, v0
	v_mov_b32_e32 v61, v0
	v_mov_b32_e32 v62, v0
	v_mov_b32_e32 v63, v0
	v_mov_b32_e32 v64, v0
	v_mov_b32_e32 v65, v0
	v_mov_b32_e32 v66, v0
	v_mov_b32_e32 v67, v0
	v_mov_b32_e32 v68, v0
	v_mov_b32_e32 v69, v0
	v_mov_b32_e32 v70, v0
	v_mov_b32_e32 v71, v0
	v_mov_b32_e32 v80, v0
	v_mov_b32_e32 v81, v0
	v_mov_b32_e32 v82, v0
	v_mov_b32_e32 v83, v0
	v_mov_b32_e32 v84, v0
	v_mov_b32_e32 v85, v0
	v_mov_b32_e32 v86, v0
	v_mov_b32_e32 v87, v0
	v_mov_b32_e32 v72, v0
	v_mov_b32_e32 v73, v0
	v_mov_b32_e32 v74, v0
	v_mov_b32_e32 v75, v0
	v_mov_b32_e32 v76, v0
	v_mov_b32_e32 v77, v0
	v_mov_b32_e32 v78, v0
	v_mov_b32_e32 v79, v0
	v_mov_b32_e32 v96, v0
	v_mov_b32_e32 v97, v0
	v_mov_b32_e32 v98, v0
	v_mov_b32_e32 v99, v0
	v_mov_b32_e32 v100, v0
	v_mov_b32_e32 v101, v0
	v_mov_b32_e32 v102, v0
	v_mov_b32_e32 v103, v0
	v_mov_b32_e32 v88, v0
	v_mov_b32_e32 v89, v0
	v_mov_b32_e32 v90, v0
	v_mov_b32_e32 v91, v0
	v_mov_b32_e32 v92, v0
	v_mov_b32_e32 v93, v0
	v_mov_b32_e32 v94, v0
	v_mov_b32_e32 v95, v0
	v_mov_b32_e32 v112, v0
	v_mov_b32_e32 v113, v0
	v_mov_b32_e32 v114, v0
	v_mov_b32_e32 v115, v0
	v_mov_b32_e32 v116, v0
	v_mov_b32_e32 v117, v0
	v_mov_b32_e32 v118, v0
	v_mov_b32_e32 v119, v0
	v_mov_b32_e32 v104, v0
	v_mov_b32_e32 v105, v0
	v_mov_b32_e32 v106, v0
	v_mov_b32_e32 v107, v0
	v_mov_b32_e32 v108, v0
	v_mov_b32_e32 v109, v0
	v_mov_b32_e32 v110, v0
	v_mov_b32_e32 v111, v0
	v_mov_b32_e32 v120, v0
	v_mov_b32_e32 v121, v0
	v_mov_b32_e32 v122, v0
	v_mov_b32_e32 v123, v0
	v_mov_b32_e32 v124, v0
	v_mov_b32_e32 v125, v0
	v_mov_b32_e32 v126, v0
	v_mov_b32_e32 v127, v0
	s_barrier
	ds_read_b128 v[140:143], v145
	ds_read_b128 v[178:181], v145 offset:1024
	ds_read_b128 v[182:185], v145 offset:2048
	ds_read_b128 v[186:189], v145 offset:3072
	v_add_u32_e32 v176, 0x4000, v147
	v_lshl_add_u64 v[162:163], v[132:133], 0, v[136:137]
	v_readfirstlane_b32 s1, v176
	v_add_u32_e32 v177, 0x6000, v147
	v_lshl_add_u64 v[164:165], v[162:163], 0, s[76:77]
	s_mov_b32 m0, s1
	v_readfirstlane_b32 s1, v177
	ds_read_b128 v[190:193], v144
	ds_read_b128 v[194:197], v144 offset:1024
	ds_read_b128 v[198:201], v144 offset:2048
	ds_read_b128 v[202:205], v144 offset:3072
	ds_read_b128 v[206:209], v144 offset:4096
	ds_read_b128 v[210:213], v144 offset:5120
	ds_read_b128 v[214:217], v144 offset:6144
	ds_read_b128 v[218:221], v144 offset:7168
	v_lshl_add_u64 v[164:165], v[162:163], 0, s[16:17]
	s_mov_b32 m0, s1
	s_nop 0
	s_waitcnt lgkmcnt(8)
	s_barrier
	s_waitcnt lgkmcnt(0)
	s_setprio 1
	s_waitcnt lgkmcnt(0)
	v_mfma_f32_16x16x32_bf16 v[124:127], v[140:143], v[190:193], v[124:127]
	v_mfma_f32_16x16x32_bf16 v[120:123], v[182:185], v[190:193], v[120:123]
	v_mfma_f32_16x16x32_bf16 v[116:119], v[140:143], v[198:201], v[116:119]
	v_mfma_f32_16x16x32_bf16 v[112:115], v[182:185], v[198:201], v[112:115]
	v_mfma_f32_16x16x32_bf16 v[100:103], v[140:143], v[206:209], v[100:103]
	v_mfma_f32_16x16x32_bf16 v[96:99], v[182:185], v[206:209], v[96:99]
	v_mfma_f32_16x16x32_bf16 v[84:87], v[140:143], v[214:217], v[84:87]
	v_mfma_f32_16x16x32_bf16 v[80:83], v[182:185], v[214:217], v[80:83]
	v_mfma_f32_16x16x32_bf16 v[124:127], v[178:181], v[194:197], v[124:127]
	v_mfma_f32_16x16x32_bf16 v[120:123], v[186:189], v[194:197], v[120:123]
	v_mfma_f32_16x16x32_bf16 v[116:119], v[178:181], v[202:205], v[116:119]
	v_mfma_f32_16x16x32_bf16 v[112:115], v[186:189], v[202:205], v[112:115]
	v_mfma_f32_16x16x32_bf16 v[100:103], v[178:181], v[210:213], v[100:103]
	v_mfma_f32_16x16x32_bf16 v[96:99], v[186:189], v[210:213], v[96:99]
	v_mfma_f32_16x16x32_bf16 v[84:87], v[178:181], v[218:221], v[84:87]
	v_mfma_f32_16x16x32_bf16 v[80:83], v[186:189], v[218:221], v[80:83]
	s_setprio 0
	s_barrier
	v_lshl_add_u64 v[164:165], v[130:131], 0, v[136:137]
	s_mov_b64 s[6:7], 0x1080100
	v_readfirstlane_b32 s1, v148
	v_lshl_add_u64 v[238:239], v[164:165], 0, s[6:7]
	s_mov_b32 m0, s1
	s_mov_b64 s[6:7], 0x10a0100
	v_readfirstlane_b32 s1, v149
	ds_read_b128 v[222:225], v145 offset:16384
	ds_read_b128 v[226:229], v145 offset:17408
	ds_read_b128 v[230:233], v145 offset:18432
	ds_read_b128 v[234:237], v145 offset:19456
	global_load_lds_dwordx4 v[238:239], off
	v_lshl_add_u64 v[238:239], v[164:165], 0, s[6:7]
	s_mov_b32 m0, s1
	s_nop 0
	global_load_lds_dwordx4 v[238:239], off
	s_barrier
	s_waitcnt lgkmcnt(0)
	s_setprio 1
	s_waitcnt lgkmcnt(0)
	v_mfma_f32_16x16x32_bf16 v[108:111], v[222:225], v[190:193], v[108:111]
	v_mfma_f32_16x16x32_bf16 v[104:107], v[230:233], v[190:193], v[104:107]
	v_mfma_f32_16x16x32_bf16 v[92:95], v[222:225], v[198:201], v[92:95]
	v_mfma_f32_16x16x32_bf16 v[88:91], v[230:233], v[198:201], v[88:91]
	v_mfma_f32_16x16x32_bf16 v[76:79], v[222:225], v[206:209], v[76:79]
	v_mfma_f32_16x16x32_bf16 v[72:75], v[230:233], v[206:209], v[72:75]
	v_mfma_f32_16x16x32_bf16 v[68:71], v[222:225], v[214:217], v[68:71]
	v_mfma_f32_16x16x32_bf16 v[64:67], v[230:233], v[214:217], v[64:67]
	v_mfma_f32_16x16x32_bf16 v[108:111], v[226:229], v[194:197], v[108:111]
	v_mfma_f32_16x16x32_bf16 v[104:107], v[234:237], v[194:197], v[104:107]
	v_mfma_f32_16x16x32_bf16 v[92:95], v[226:229], v[202:205], v[92:95]
	v_mfma_f32_16x16x32_bf16 v[88:91], v[234:237], v[202:205], v[88:91]
	v_mfma_f32_16x16x32_bf16 v[76:79], v[226:229], v[210:213], v[76:79]
	v_mfma_f32_16x16x32_bf16 v[72:75], v[234:237], v[210:213], v[72:75]
	v_mfma_f32_16x16x32_bf16 v[68:71], v[226:229], v[218:221], v[68:71]
	v_mfma_f32_16x16x32_bf16 v[64:67], v[234:237], v[218:221], v[64:67]
	s_setprio 0
	v_readfirstlane_b32 s1, v146
	v_lshl_add_u64 v[238:239], v[162:163], 0, s[88:89]
	s_mov_b32 m0, s1
	v_readfirstlane_b32 s1, v150
	s_barrier
	ds_read_b128 v[190:193], v144 offset:16384
	ds_read_b128 v[194:197], v144 offset:17408
	ds_read_b128 v[198:201], v144 offset:18432
	ds_read_b128 v[202:205], v144 offset:19456
	ds_read_b128 v[206:209], v144 offset:20480
	ds_read_b128 v[210:213], v144 offset:21504
	ds_read_b128 v[214:217], v144 offset:22528
	ds_read_b128 v[218:221], v144 offset:23552
	global_load_lds_dwordx4 v[238:239], off
	v_lshl_add_u64 v[238:239], v[162:163], 0, s[90:91]
	s_mov_b32 m0, s1
	s_nop 0
	global_load_lds_dwordx4 v[238:239], off
	s_barrier
	s_waitcnt lgkmcnt(0)
	s_setprio 1
	s_waitcnt lgkmcnt(0)
	v_mfma_f32_16x16x32_bf16 v[60:63], v[140:143], v[190:193], v[60:63]
	v_mfma_f32_16x16x32_bf16 v[56:59], v[182:185], v[190:193], v[56:59]
	v_mfma_f32_16x16x32_bf16 v[52:55], v[140:143], v[198:201], v[52:55]
	v_mfma_f32_16x16x32_bf16 v[44:47], v[182:185], v[198:201], v[44:47]
	v_mfma_f32_16x16x32_bf16 v[36:39], v[140:143], v[206:209], v[36:39]
	v_mfma_f32_16x16x32_bf16 v[28:31], v[182:185], v[206:209], v[28:31]
	v_mfma_f32_16x16x32_bf16 v[20:23], v[140:143], v[214:217], v[20:23]
	v_mfma_f32_16x16x32_bf16 v[12:15], v[182:185], v[214:217], v[12:15]
	v_mfma_f32_16x16x32_bf16 v[60:63], v[178:181], v[194:197], v[60:63]
	v_mfma_f32_16x16x32_bf16 v[56:59], v[186:189], v[194:197], v[56:59]
	v_mfma_f32_16x16x32_bf16 v[52:55], v[178:181], v[202:205], v[52:55]
	v_mfma_f32_16x16x32_bf16 v[44:47], v[186:189], v[202:205], v[44:47]
	v_mfma_f32_16x16x32_bf16 v[36:39], v[178:181], v[210:213], v[36:39]
	v_mfma_f32_16x16x32_bf16 v[28:31], v[186:189], v[210:213], v[28:31]
	v_mfma_f32_16x16x32_bf16 v[20:23], v[178:181], v[218:221], v[20:23]
	v_mfma_f32_16x16x32_bf16 v[12:15], v[186:189], v[218:221], v[12:15]
	s_setprio 0
	s_barrier
	s_mov_b64 s[6:7], 0x10c0100
	v_readfirstlane_b32 s1, v151
	v_lshl_add_u64 v[140:141], v[164:165], 0, s[6:7]
	s_mov_b32 m0, s1
	s_mov_b64 s[6:7], 0x10e0100
	v_readfirstlane_b32 s1, v152
	global_load_lds_dwordx4 v[140:141], off
	v_lshl_add_u64 v[140:141], v[164:165], 0, s[6:7]
	s_mov_b32 m0, s1
	s_nop 0
	global_load_lds_dwordx4 v[140:141], off
	s_waitcnt vmcnt(22)
	s_barrier
	s_setprio 1
	v_mfma_f32_16x16x32_bf16 v[48:51], v[222:225], v[190:193], v[48:51]
	v_mfma_f32_16x16x32_bf16 v[40:43], v[230:233], v[190:193], v[40:43]
	v_mfma_f32_16x16x32_bf16 v[32:35], v[222:225], v[198:201], v[32:35]
	v_mfma_f32_16x16x32_bf16 v[24:27], v[230:233], v[198:201], v[24:27]
	v_mfma_f32_16x16x32_bf16 v[16:19], v[222:225], v[206:209], v[16:19]
	v_mfma_f32_16x16x32_bf16 v[8:11], v[230:233], v[206:209], v[8:11]
	v_mfma_f32_16x16x32_bf16 v[4:7], v[222:225], v[214:217], v[4:7]
	v_mfma_f32_16x16x32_bf16 v[0:3], v[230:233], v[214:217], v[0:3]
	v_mfma_f32_16x16x32_bf16 v[48:51], v[226:229], v[194:197], v[48:51]
	v_mfma_f32_16x16x32_bf16 v[40:43], v[234:237], v[194:197], v[40:43]
	v_mfma_f32_16x16x32_bf16 v[32:35], v[226:229], v[202:205], v[32:35]
	v_mfma_f32_16x16x32_bf16 v[24:27], v[234:237], v[202:205], v[24:27]
	v_mfma_f32_16x16x32_bf16 v[16:19], v[226:229], v[210:213], v[16:19]
	v_mfma_f32_16x16x32_bf16 v[8:11], v[234:237], v[210:213], v[8:11]
	v_mfma_f32_16x16x32_bf16 v[4:7], v[226:229], v[218:221], v[4:7]
	v_mfma_f32_16x16x32_bf16 v[0:3], v[234:237], v[218:221], v[0:3]
	s_setprio 0
	s_barrier
	ds_read_b128 v[140:143], v139
	ds_read_b128 v[178:181], v139 offset:1024
	ds_read_b128 v[182:185], v139 offset:2048
	ds_read_b128 v[186:189], v139 offset:3072
	v_readfirstlane_b32 s1, v153
	v_lshl_add_u64 v[222:223], v[162:163], 0, s[94:95]
	s_mov_b32 m0, s1
	v_readfirstlane_b32 s1, v170
	ds_read_b128 v[190:193], v135
	ds_read_b128 v[194:197], v135 offset:1024
	ds_read_b128 v[198:201], v135 offset:2048
	ds_read_b128 v[202:205], v135 offset:3072
	ds_read_b128 v[206:209], v135 offset:4096
	ds_read_b128 v[210:213], v135 offset:5120
	ds_read_b128 v[214:217], v135 offset:6144
	ds_read_b128 v[218:221], v135 offset:7168
	global_load_lds_dwordx4 v[222:223], off
	v_lshl_add_u64 v[222:223], v[162:163], 0, s[78:79]
	s_mov_b32 m0, s1
	s_nop 0
	global_load_lds_dwordx4 v[222:223], off
	s_waitcnt lgkmcnt(8)
	s_barrier
	s_waitcnt lgkmcnt(0)
	s_setprio 1
	s_waitcnt lgkmcnt(0)
	v_mfma_f32_16x16x32_bf16 v[124:127], v[140:143], v[190:193], v[124:127]
	v_mfma_f32_16x16x32_bf16 v[120:123], v[182:185], v[190:193], v[120:123]
	v_mfma_f32_16x16x32_bf16 v[116:119], v[140:143], v[198:201], v[116:119]
	v_mfma_f32_16x16x32_bf16 v[112:115], v[182:185], v[198:201], v[112:115]
	v_mfma_f32_16x16x32_bf16 v[100:103], v[140:143], v[206:209], v[100:103]
	v_mfma_f32_16x16x32_bf16 v[96:99], v[182:185], v[206:209], v[96:99]
	v_mfma_f32_16x16x32_bf16 v[84:87], v[140:143], v[214:217], v[84:87]
	v_mfma_f32_16x16x32_bf16 v[80:83], v[182:185], v[214:217], v[80:83]
	v_mfma_f32_16x16x32_bf16 v[124:127], v[178:181], v[194:197], v[124:127]
	v_mfma_f32_16x16x32_bf16 v[120:123], v[186:189], v[194:197], v[120:123]
	v_mfma_f32_16x16x32_bf16 v[116:119], v[178:181], v[202:205], v[116:119]
	v_mfma_f32_16x16x32_bf16 v[112:115], v[186:189], v[202:205], v[112:115]
	v_mfma_f32_16x16x32_bf16 v[100:103], v[178:181], v[210:213], v[100:103]
	v_mfma_f32_16x16x32_bf16 v[96:99], v[186:189], v[210:213], v[96:99]
	v_mfma_f32_16x16x32_bf16 v[84:87], v[178:181], v[218:221], v[84:87]
	v_mfma_f32_16x16x32_bf16 v[80:83], v[186:189], v[218:221], v[80:83]
	s_setprio 0
	s_barrier
	s_mov_b64 s[6:7], 0x1080180
	v_readfirstlane_b32 s1, v171
	v_lshl_add_u64 v[238:239], v[164:165], 0, s[6:7]
	s_mov_b32 m0, s1
	s_mov_b64 s[6:7], 0x10a0180
	v_readfirstlane_b32 s1, v172
	ds_read_b128 v[222:225], v139 offset:16384
	ds_read_b128 v[226:229], v139 offset:17408
	ds_read_b128 v[230:233], v139 offset:18432
	ds_read_b128 v[234:237], v139 offset:19456
	global_load_lds_dwordx4 v[238:239], off
	v_lshl_add_u64 v[238:239], v[164:165], 0, s[6:7]
	s_mov_b32 m0, s1
	s_nop 0
	global_load_lds_dwordx4 v[238:239], off
	s_barrier
	s_waitcnt lgkmcnt(0)
	s_setprio 1
	s_waitcnt lgkmcnt(0)
	v_mfma_f32_16x16x32_bf16 v[108:111], v[222:225], v[190:193], v[108:111]
	v_mfma_f32_16x16x32_bf16 v[104:107], v[230:233], v[190:193], v[104:107]
	v_mfma_f32_16x16x32_bf16 v[92:95], v[222:225], v[198:201], v[92:95]
	v_mfma_f32_16x16x32_bf16 v[88:91], v[230:233], v[198:201], v[88:91]
	v_mfma_f32_16x16x32_bf16 v[76:79], v[222:225], v[206:209], v[76:79]
	v_mfma_f32_16x16x32_bf16 v[72:75], v[230:233], v[206:209], v[72:75]
	v_mfma_f32_16x16x32_bf16 v[68:71], v[222:225], v[214:217], v[68:71]
	v_mfma_f32_16x16x32_bf16 v[64:67], v[230:233], v[214:217], v[64:67]
	v_mfma_f32_16x16x32_bf16 v[108:111], v[226:229], v[194:197], v[108:111]
	v_mfma_f32_16x16x32_bf16 v[104:107], v[234:237], v[194:197], v[104:107]
	v_mfma_f32_16x16x32_bf16 v[92:95], v[226:229], v[202:205], v[92:95]
	v_mfma_f32_16x16x32_bf16 v[88:91], v[234:237], v[202:205], v[88:91]
	v_mfma_f32_16x16x32_bf16 v[76:79], v[226:229], v[210:213], v[76:79]
	v_mfma_f32_16x16x32_bf16 v[72:75], v[234:237], v[210:213], v[72:75]
	v_mfma_f32_16x16x32_bf16 v[68:71], v[226:229], v[218:221], v[68:71]
	v_mfma_f32_16x16x32_bf16 v[64:67], v[234:237], v[218:221], v[64:67]
	s_setprio 0
	v_readfirstlane_b32 s1, v147
	v_lshl_add_u64 v[238:239], v[162:163], 0, s[24:25]
	s_mov_b32 m0, s1
	v_readfirstlane_b32 s1, v173
	s_barrier
	ds_read_b128 v[190:193], v135 offset:16384
	ds_read_b128 v[194:197], v135 offset:17408
	ds_read_b128 v[198:201], v135 offset:18432
	ds_read_b128 v[202:205], v135 offset:19456
	ds_read_b128 v[206:209], v135 offset:20480
	ds_read_b128 v[210:213], v135 offset:21504
	ds_read_b128 v[214:217], v135 offset:22528
	ds_read_b128 v[218:221], v135 offset:23552
	global_load_lds_dwordx4 v[238:239], off
	v_lshl_add_u64 v[162:163], v[162:163], 0, s[28:29]
	s_mov_b32 m0, s1
	s_nop 0
	global_load_lds_dwordx4 v[162:163], off
	s_barrier
	s_waitcnt lgkmcnt(0)
	s_setprio 1
	s_waitcnt lgkmcnt(0)
	v_mfma_f32_16x16x32_bf16 v[60:63], v[140:143], v[190:193], v[60:63]
	v_mfma_f32_16x16x32_bf16 v[56:59], v[182:185], v[190:193], v[56:59]
	v_mfma_f32_16x16x32_bf16 v[52:55], v[140:143], v[198:201], v[52:55]
	v_mfma_f32_16x16x32_bf16 v[44:47], v[182:185], v[198:201], v[44:47]
	v_mfma_f32_16x16x32_bf16 v[36:39], v[140:143], v[206:209], v[36:39]
	v_mfma_f32_16x16x32_bf16 v[28:31], v[182:185], v[206:209], v[28:31]
	v_mfma_f32_16x16x32_bf16 v[20:23], v[140:143], v[214:217], v[20:23]
	v_mfma_f32_16x16x32_bf16 v[12:15], v[182:185], v[214:217], v[12:15]
	v_mfma_f32_16x16x32_bf16 v[60:63], v[178:181], v[194:197], v[60:63]
	v_mfma_f32_16x16x32_bf16 v[56:59], v[186:189], v[194:197], v[56:59]
	v_mfma_f32_16x16x32_bf16 v[52:55], v[178:181], v[202:205], v[52:55]
	v_mfma_f32_16x16x32_bf16 v[44:47], v[186:189], v[202:205], v[44:47]
	v_mfma_f32_16x16x32_bf16 v[36:39], v[178:181], v[210:213], v[36:39]
	v_mfma_f32_16x16x32_bf16 v[28:31], v[186:189], v[210:213], v[28:31]
	v_mfma_f32_16x16x32_bf16 v[20:23], v[178:181], v[218:221], v[20:23]
	v_mfma_f32_16x16x32_bf16 v[12:15], v[186:189], v[218:221], v[12:15]
	s_setprio 0
	s_barrier
	s_mov_b64 s[6:7], 0x10c0180
	v_readfirstlane_b32 s1, v174
	v_lshl_add_u64 v[140:141], v[164:165], 0, s[6:7]
	s_mov_b32 m0, s1
	s_mov_b64 s[6:7], 0x10e0180
	v_readfirstlane_b32 s1, v175
	global_load_lds_dwordx4 v[140:141], off
	v_lshl_add_u64 v[140:141], v[164:165], 0, s[6:7]
	s_mov_b32 m0, s1
	s_nop 0
	global_load_lds_dwordx4 v[140:141], off
	s_waitcnt vmcnt(6)
	s_barrier
	s_setprio 1
	v_mfma_f32_16x16x32_bf16 v[48:51], v[222:225], v[190:193], v[48:51]
	v_mfma_f32_16x16x32_bf16 v[40:43], v[230:233], v[190:193], v[40:43]
	v_mfma_f32_16x16x32_bf16 v[32:35], v[222:225], v[198:201], v[32:35]
	v_mfma_f32_16x16x32_bf16 v[24:27], v[230:233], v[198:201], v[24:27]
	v_mfma_f32_16x16x32_bf16 v[16:19], v[222:225], v[206:209], v[16:19]
	v_mfma_f32_16x16x32_bf16 v[8:11], v[230:233], v[206:209], v[8:11]
	v_mfma_f32_16x16x32_bf16 v[4:7], v[222:225], v[214:217], v[4:7]
	v_mfma_f32_16x16x32_bf16 v[0:3], v[230:233], v[214:217], v[0:3]
	v_mfma_f32_16x16x32_bf16 v[48:51], v[226:229], v[194:197], v[48:51]
	v_mfma_f32_16x16x32_bf16 v[40:43], v[234:237], v[194:197], v[40:43]
	v_mfma_f32_16x16x32_bf16 v[32:35], v[226:229], v[202:205], v[32:35]
	v_mfma_f32_16x16x32_bf16 v[24:27], v[234:237], v[202:205], v[24:27]
	v_mfma_f32_16x16x32_bf16 v[16:19], v[226:229], v[210:213], v[16:19]
	v_mfma_f32_16x16x32_bf16 v[8:11], v[234:237], v[210:213], v[8:11]
	v_mfma_f32_16x16x32_bf16 v[4:7], v[226:229], v[218:221], v[4:7]
	v_mfma_f32_16x16x32_bf16 v[0:3], v[234:237], v[218:221], v[0:3]
	s_setprio 0
	s_add_i32 s0, s0, 2
	v_lshl_add_u64 v[130:131], v[130:131], 0, s[86:87]
	s_cmp_gt_u32 s0, 11
	v_lshl_add_u64 v[132:133], v[132:133], 0, s[86:87]
	s_barrier
	s_branch .LBB0_225

.LBB0_659:
	s_or_b64 exec, exec, s[4:5]
	s_add_i32 s36, s8, s74
	s_cmpk_gt_i32 s36, 0x57f
	s_cbranch_scc1 .Lt2_skip_up2
	s_lshl_b32 s37, s36, 3
	s_and_b32 s37, s37, 56
	s_bfe_u32 s43, s36, 0x30003
	s_or_b32 s37, s37, s43
	s_lshl_b32 s37, s37, 19
	v_readlane_b32 s38, v253, 47
	v_readlane_b32 s39, v253, 48
	s_add_u32 s38, s38, s37
	s_addc_u32 s39, s39, 0
	s_ashr_i32 s43, s36, 6
	s_lshl_b32 s43, s43, 19
	s_add_u32 s40, s9, s43
	s_addc_u32 s41, s10, 0
	v_lshrrev_b32_e32 v243, 7, v154
	v_bfe_u32 v244, v154, 2, 4
	v_lshl_add_u32 v243, v243, 4, v244
	v_bfe_u32 v244, v154, 5, 1
	v_lshlrev_b32_e32 v244, 1, v244
	v_and_b32_e32 v245, 3, v154
	v_xor_b32_e32 v244, v244, v245
	v_lshlrev_b32_e32 v244, 4, v244
	v_bfe_u32 v245, v154, 6, 1
	v_lshl_or_b32 v244, v245, 6, v244
	v_lshl_or_b32 v242, v243, 11, v244
	v_lshrrev_b32_e32 v245, 6, v154
	v_lshlrev_b32_e32 v245, 10, v245
	s_nop 0
	v_readfirstlane_b32 s42, v245
	s_add_u32 m0, s42, 0x8000
	s_nop 0
	global_load_lds_dwordx4 v242, s[40:41]
	s_add_u32 m0, s42, 0xa000
	s_add_u32 s40, s40, 0x20000
	s_addc_u32 s41, s41, 0
	global_load_lds_dwordx4 v242, s[40:41]
	s_add_u32 m0, s42, 0x0
	s_nop 0
	global_load_lds_dwordx4 v242, s[38:39]
	s_add_u32 m0, s42, 0x2000
	s_add_u32 s38, s38, 0x20000
	s_addc_u32 s39, s39, 0
	global_load_lds_dwordx4 v242, s[38:39]
	s_add_u32 m0, s42, 0xc000
	s_add_u32 s40, s40, 0x20000
	s_addc_u32 s41, s41, 0
	global_load_lds_dwordx4 v242, s[40:41]
	s_add_u32 m0, s42, 0xe000
	s_add_u32 s40, s40, 0x20000
	s_addc_u32 s41, s41, 0
	global_load_lds_dwordx4 v242, s[40:41]
	s_add_u32 m0, s42, 0x4000
	s_add_u32 s38, s38, 0x20000
	s_addc_u32 s39, s39, 0
	global_load_lds_dwordx4 v242, s[38:39]
	s_add_u32 m0, s42, 0x6000
	s_add_u32 s38, s38, 0x20000
	s_addc_u32 s39, s39, 0
	global_load_lds_dwordx4 v242, s[38:39]
	s_add_u32 m0, s42, 0x18000
	s_sub_u32 s40, s40, 0x5ff80
	s_subb_u32 s41, s41, 0
	global_load_lds_dwordx4 v242, s[40:41]
	s_add_u32 m0, s42, 0x1a000
	s_add_u32 s40, s40, 0x20000
	s_addc_u32 s41, s41, 0
	global_load_lds_dwordx4 v242, s[40:41]
	s_add_u32 m0, s42, 0x10000
	s_sub_u32 s38, s38, 0x5ff80
	s_subb_u32 s39, s39, 0
	global_load_lds_dwordx4 v242, s[38:39]
	s_add_u32 m0, s42, 0x12000
	s_add_u32 s38, s38, 0x20000
	s_addc_u32 s39, s39, 0
	global_load_lds_dwordx4 v242, s[38:39]
	s_add_u32 m0, s42, 0x1c000
	s_add_u32 s40, s40, 0x20000
	s_addc_u32 s41, s41, 0
	global_load_lds_dwordx4 v242, s[40:41]
	s_add_u32 m0, s42, 0x1e000
	s_add_u32 s40, s40, 0x20000
	s_addc_u32 s41, s41, 0
	global_load_lds_dwordx4 v242, s[40:41]
	s_add_u32 m0, s42, 0x14000
	s_add_u32 s38, s38, 0x20000
	s_addc_u32 s39, s39, 0
	global_load_lds_dwordx4 v242, s[38:39]
	s_add_u32 m0, s42, 0x16000
	s_add_u32 s38, s38, 0x20000
	s_addc_u32 s39, s39, 0
	global_load_lds_dwordx4 v242, s[38:39]
.Lt2_skip_up2:
	v_mov_b32_e32 v128, v154
	v_mul_f32_e32 v130, 0xbfb8aa3b, v121
	v_ashrrev_i32_e32 v129, 2, v128
	v_and_b32_e32 v129, 0xffffffc0, v129
	v_lshl_add_u32 v129, s12, 8, v129
	v_and_or_b32 v132, v128, 15, v129
	v_mul_f32_e32 v129, 0xbfb8aa3b, v120
	v_exp_f32_e32 v129, v129
	v_exp_f32_e32 v130, v130
	v_lshrrev_b32_e32 v131, 1, v128
	s_add_i32 s8, s8, s74
	v_add_f32_e32 v128, 1.0, v129
	v_add_f32_e32 v129, 1.0, v130
	v_rcp_f32_e32 v128, v128
	v_rcp_f32_e32 v129, v129
	v_and_b32_e32 v130, 0x78, v131
	v_lshl_or_b32 v130, s0, 7, v130
	v_readlane_b32 s0, v253, 49
	v_pk_mul_f32 v[120:121], v[120:121], v[128:129]
	v_mul_f32_e32 v128, 0xbfb8aa3b, v122
	v_mul_f32_e32 v129, 0xbfb8aa3b, v123
	v_exp_f32_e32 v128, v128
	v_exp_f32_e32 v129, v129
	v_pk_mul_f32 v[120:121], v[120:121], v[124:125]
	v_readlane_b32 s1, v253, 50
	v_add_f32_e32 v124, 1.0, v128
	v_add_f32_e32 v125, 1.0, v129
	v_mul_f32_e32 v128, 0xbfb8aa3b, v112
	v_mul_f32_e32 v129, 0xbfb8aa3b, v113
	v_rcp_f32_e32 v124, v124
	v_rcp_f32_e32 v125, v125
	v_exp_f32_e32 v128, v128
	v_exp_f32_e32 v129, v129
	v_ashrrev_i32_e32 v131, 31, v130
	v_pk_mul_f32 v[122:123], v[122:123], v[124:125]
	v_add_f32_e32 v124, 1.0, v128
	v_add_f32_e32 v125, 1.0, v129
	v_mul_f32_e32 v128, 0xbfb8aa3b, v114
	v_mul_f32_e32 v129, 0xbfb8aa3b, v115
	v_exp_f32_e32 v128, v128
	v_exp_f32_e32 v129, v129
	v_rcp_f32_e32 v124, v124
	v_rcp_f32_e32 v125, v125
	v_add_f32_e32 v128, 1.0, v128
	v_add_f32_e32 v129, 1.0, v129
	v_rcp_f32_e32 v128, v128
	v_rcp_f32_e32 v129, v129
	v_pk_mul_f32 v[112:113], v[112:113], v[124:125]
	v_pk_mul_f32 v[122:123], v[122:123], v[126:127]
	v_pk_mul_f32 v[112:113], v[112:113], v[116:117]
	v_pk_mul_f32 v[114:115], v[114:115], v[128:129]
	v_cvt_pk_bf16_f32 v116, v120, v121
	v_pk_mul_f32 v[114:115], v[114:115], v[118:119]
	v_cvt_pk_bf16_f32 v118, v112, v113
	v_cvt_pk_bf16_f32 v119, v114, v115
	v_mul_f32_e32 v114, 0xbfb8aa3b, v104
	v_exp_f32_e32 v114, v114
	v_mul_f32_e32 v115, 0xbfb8aa3b, v105
	v_exp_f32_e32 v115, v115
	v_mov_b64_e32 v[112:113], s[0:1]
	v_add_f32_e32 v114, 1.0, v114
	v_rcp_f32_e32 v120, v114
	v_add_f32_e32 v114, 1.0, v115
	v_mad_i64_i32 v[112:113], s[0:1], v132, s33, v[112:113]
	v_rcp_f32_e32 v121, v114
	v_lshlrev_b64 v[114:115], 1, v[130:131]
	v_cvt_pk_bf16_f32 v117, v122, v123
	v_lshl_add_u64 v[112:113], v[112:113], 0, v[114:115]
	global_store_dwordx4 v[112:113], v[116:119], off
	v_pk_mul_f32 v[104:105], v[104:105], v[120:121]
	v_readlane_b32 s0, v253, 51
	v_mul_f32_e32 v116, 0xbfb8aa3b, v106
	v_mul_f32_e32 v117, 0xbfb8aa3b, v107
	v_exp_f32_e32 v116, v116
	v_exp_f32_e32 v117, v117
	v_pk_mul_f32 v[104:105], v[104:105], v[108:109]
	v_readlane_b32 s1, v253, 52
	v_add_f32_e32 v108, 1.0, v116
	v_add_f32_e32 v109, 1.0, v117
	v_mul_f32_e32 v116, 0xbfb8aa3b, v96
	v_mul_f32_e32 v117, 0xbfb8aa3b, v97
	v_rcp_f32_e32 v108, v108
	v_rcp_f32_e32 v109, v109
	v_exp_f32_e32 v116, v116
	v_exp_f32_e32 v117, v117
	s_add_i32 s11, s11, s20
	v_pk_mul_f32 v[106:107], v[106:107], v[108:109]
	v_add_f32_e32 v108, 1.0, v116
	v_add_f32_e32 v109, 1.0, v117
	v_mul_f32_e32 v116, 0xbfb8aa3b, v98
	v_mul_f32_e32 v117, 0xbfb8aa3b, v99
	v_exp_f32_e32 v116, v116
	v_exp_f32_e32 v117, v117
	v_rcp_f32_e32 v108, v108
	v_rcp_f32_e32 v109, v109
	v_add_f32_e32 v116, 1.0, v116
	v_add_f32_e32 v117, 1.0, v117
	v_rcp_f32_e32 v116, v116
	v_rcp_f32_e32 v117, v117
	v_pk_mul_f32 v[96:97], v[96:97], v[108:109]
	v_pk_mul_f32 v[106:107], v[106:107], v[110:111]
	v_pk_mul_f32 v[96:97], v[96:97], v[100:101]
	v_pk_mul_f32 v[98:99], v[98:99], v[116:117]
	v_cvt_pk_bf16_f32 v100, v96, v97
	v_pk_mul_f32 v[102:103], v[98:99], v[102:103]
	v_mul_f32_e32 v96, 0xbfb8aa3b, v88
	v_cvt_pk_bf16_f32 v101, v102, v103
	v_exp_f32_e32 v102, v96
	v_mul_f32_e32 v96, 0xbfb8aa3b, v89
	v_exp_f32_e32 v103, v96
	v_mov_b64_e32 v[96:97], s[0:1]
	v_mad_i64_i32 v[96:97], s[0:1], v132, s33, v[96:97]
	v_cvt_pk_bf16_f32 v98, v104, v105
	v_cvt_pk_bf16_f32 v99, v106, v107
	v_add_f32_e32 v102, 1.0, v102
	v_add_f32_e32 v103, 1.0, v103
	v_lshl_add_u64 v[96:97], v[96:97], 0, v[114:115]
	v_rcp_f32_e32 v102, v102
	v_rcp_f32_e32 v103, v103
	global_store_dwordx4 v[96:97], v[98:101], off
	v_readlane_b32 s0, v253, 53
	v_readlane_b32 s1, v253, 54
	v_mul_f32_e32 v98, 0xbfb8aa3b, v90
	v_mul_f32_e32 v99, 0xbfb8aa3b, v91
	v_exp_f32_e32 v98, v98
	v_exp_f32_e32 v99, v99
	v_pk_mul_f32 v[88:89], v[88:89], v[102:103]
	s_cmpk_lt_i32 s8, 0x580
	v_pk_mul_f32 v[88:89], v[88:89], v[92:93]
	v_add_f32_e32 v92, 1.0, v98
	v_add_f32_e32 v93, 1.0, v99
	v_mul_f32_e32 v98, 0xbfb8aa3b, v80
	v_mul_f32_e32 v99, 0xbfb8aa3b, v81
	v_rcp_f32_e32 v92, v92
	v_rcp_f32_e32 v93, v93
	v_exp_f32_e32 v98, v98
	v_exp_f32_e32 v99, v99
	v_pk_mul_f32 v[90:91], v[90:91], v[92:93]
	v_add_f32_e32 v92, 1.0, v98
	v_add_f32_e32 v93, 1.0, v99
	v_mul_f32_e32 v98, 0xbfb8aa3b, v82
	v_mul_f32_e32 v99, 0xbfb8aa3b, v83
	v_exp_f32_e32 v98, v98
	v_exp_f32_e32 v99, v99
	v_rcp_f32_e32 v92, v92
	v_rcp_f32_e32 v93, v93
	v_add_f32_e32 v98, 1.0, v98
	v_add_f32_e32 v99, 1.0, v99
	v_rcp_f32_e32 v98, v98
	v_rcp_f32_e32 v99, v99
	v_pk_mul_f32 v[80:81], v[80:81], v[92:93]
	v_pk_mul_f32 v[90:91], v[90:91], v[94:95]
	v_pk_mul_f32 v[80:81], v[80:81], v[84:85]
	v_pk_mul_f32 v[82:83], v[82:83], v[98:99]
	v_cvt_pk_bf16_f32 v84, v80, v81
	v_pk_mul_f32 v[86:87], v[82:83], v[86:87]
	v_mul_f32_e32 v80, 0xbfb8aa3b, v72
	v_cvt_pk_bf16_f32 v85, v86, v87
	v_exp_f32_e32 v86, v80
	v_mul_f32_e32 v80, 0xbfb8aa3b, v73
	v_exp_f32_e32 v87, v80
	v_mov_b64_e32 v[80:81], s[0:1]
	v_mad_i64_i32 v[80:81], s[0:1], v132, s33, v[80:81]
	v_cvt_pk_bf16_f32 v82, v88, v89
	v_cvt_pk_bf16_f32 v83, v90, v91
	v_add_f32_e32 v86, 1.0, v86
	v_add_f32_e32 v87, 1.0, v87
	v_lshl_add_u64 v[80:81], v[80:81], 0, v[114:115]
	v_rcp_f32_e32 v86, v86
	v_rcp_f32_e32 v87, v87
	global_store_dwordx4 v[80:81], v[82:85], off
	v_readlane_b32 s0, v253, 55
	v_readlane_b32 s1, v253, 56
	v_mul_f32_e32 v82, 0xbfb8aa3b, v74
	v_mul_f32_e32 v83, 0xbfb8aa3b, v75
	v_exp_f32_e32 v82, v82
	v_exp_f32_e32 v83, v83
	v_pk_mul_f32 v[72:73], v[72:73], v[86:87]
	s_nop 0
	v_pk_mul_f32 v[72:73], v[72:73], v[76:77]
	v_add_f32_e32 v76, 1.0, v82
	v_add_f32_e32 v77, 1.0, v83
	v_mul_f32_e32 v82, 0xbfb8aa3b, v64
	v_mul_f32_e32 v83, 0xbfb8aa3b, v65
	v_rcp_f32_e32 v76, v76
	v_rcp_f32_e32 v77, v77
	v_exp_f32_e32 v82, v82
	v_exp_f32_e32 v83, v83
	v_pk_mul_f32 v[74:75], v[74:75], v[76:77]
	v_add_f32_e32 v76, 1.0, v82
	v_add_f32_e32 v77, 1.0, v83
	v_mul_f32_e32 v82, 0xbfb8aa3b, v66
	v_mul_f32_e32 v83, 0xbfb8aa3b, v67
	v_exp_f32_e32 v82, v82
	v_exp_f32_e32 v83, v83
	v_rcp_f32_e32 v76, v76
	v_rcp_f32_e32 v77, v77
	v_add_f32_e32 v82, 1.0, v82
	v_add_f32_e32 v83, 1.0, v83
	v_rcp_f32_e32 v82, v82
	v_rcp_f32_e32 v83, v83
	v_pk_mul_f32 v[64:65], v[64:65], v[76:77]
	v_pk_mul_f32 v[74:75], v[74:75], v[78:79]
	v_pk_mul_f32 v[64:65], v[64:65], v[68:69]
	v_pk_mul_f32 v[66:67], v[66:67], v[82:83]
	v_cvt_pk_bf16_f32 v68, v64, v65
	v_pk_mul_f32 v[70:71], v[66:67], v[70:71]
	v_mul_f32_e32 v64, 0xbfb8aa3b, v60
	v_cvt_pk_bf16_f32 v69, v70, v71
	v_exp_f32_e32 v70, v64
	v_mul_f32_e32 v64, 0xbfb8aa3b, v61
	v_exp_f32_e32 v71, v64
	v_mov_b64_e32 v[64:65], s[0:1]
	v_mad_i64_i32 v[64:65], s[0:1], v132, s33, v[64:65]
	v_cvt_pk_bf16_f32 v66, v72, v73
	v_cvt_pk_bf16_f32 v67, v74, v75
	v_add_f32_e32 v70, 1.0, v70
	v_add_f32_e32 v71, 1.0, v71
	v_lshl_add_u64 v[64:65], v[64:65], 0, v[114:115]
	v_rcp_f32_e32 v70, v70
	v_rcp_f32_e32 v71, v71
	global_store_dwordx4 v[64:65], v[66:69], off
	s_mov_b32 s0, 0xb0000
	v_pk_mul_f32 v[60:61], v[60:61], v[70:71]
	v_mul_f32_e32 v66, 0xbfb8aa3b, v62
	v_mul_f32_e32 v67, 0xbfb8aa3b, v63
	v_exp_f32_e32 v66, v66
	v_exp_f32_e32 v67, v67
	v_pk_mul_f32 v[56:57], v[60:61], v[56:57]
	v_add_f32_e32 v60, 1.0, v66
	v_add_f32_e32 v61, 1.0, v67
	v_mul_f32_e32 v66, 0xbfb8aa3b, v48
	v_mul_f32_e32 v67, 0xbfb8aa3b, v49
	v_rcp_f32_e32 v60, v60
	v_rcp_f32_e32 v61, v61
	v_exp_f32_e32 v66, v66
	v_exp_f32_e32 v67, v67
	v_pk_mul_f32 v[60:61], v[62:63], v[60:61]
	v_add_f32_e32 v62, 1.0, v66
	v_add_f32_e32 v63, 1.0, v67
	v_mul_f32_e32 v66, 0xbfb8aa3b, v50
	v_mul_f32_e32 v67, 0xbfb8aa3b, v51
	v_exp_f32_e32 v66, v66
	v_exp_f32_e32 v67, v67
	v_rcp_f32_e32 v62, v62
	v_rcp_f32_e32 v63, v63
	v_add_f32_e32 v66, 1.0, v66
	v_add_f32_e32 v67, 1.0, v67
	v_rcp_f32_e32 v66, v66
	v_rcp_f32_e32 v67, v67
	v_pk_mul_f32 v[48:49], v[48:49], v[62:63]
	v_pk_mul_f32 v[58:59], v[60:61], v[58:59]
	v_pk_mul_f32 v[52:53], v[48:49], v[52:53]
	v_pk_mul_f32 v[48:49], v[50:51], v[66:67]
	v_mul_f32_e32 v51, 0xbfb8aa3b, v44
	v_cvt_pk_bf16_f32 v50, v52, v53
	v_exp_f32_e32 v52, v51
	v_mul_f32_e32 v51, 0xbfb8aa3b, v45
	v_exp_f32_e32 v53, v51
	v_pk_mul_f32 v[54:55], v[48:49], v[54:55]
	v_cvt_pk_bf16_f32 v48, v56, v57
	v_cvt_pk_bf16_f32 v51, v54, v55
	v_add_co_u32_e32 v54, vcc, s0, v112
	v_cvt_pk_bf16_f32 v49, v58, v59
	v_add_f32_e32 v52, 1.0, v52
	v_add_f32_e32 v53, 1.0, v53
	v_addc_co_u32_e32 v55, vcc, 0, v113, vcc
	v_rcp_f32_e32 v52, v52
	v_rcp_f32_e32 v53, v53
	global_store_dwordx4 v[54:55], v[48:51], off
	v_pk_mul_f32 v[44:45], v[44:45], v[52:53]
	s_nop 0
	v_mul_f32_e32 v48, 0xbfb8aa3b, v46
	v_mul_f32_e32 v49, 0xbfb8aa3b, v47
	v_exp_f32_e32 v48, v48
	v_exp_f32_e32 v49, v49
	v_pk_mul_f32 v[40:41], v[44:45], v[40:41]
	v_add_f32_e32 v44, 1.0, v48
	v_add_f32_e32 v45, 1.0, v49
	v_mul_f32_e32 v48, 0xbfb8aa3b, v32
	v_mul_f32_e32 v49, 0xbfb8aa3b, v33
	v_rcp_f32_e32 v44, v44
	v_rcp_f32_e32 v45, v45
	v_exp_f32_e32 v48, v48
	v_exp_f32_e32 v49, v49
	v_pk_mul_f32 v[44:45], v[46:47], v[44:45]
	v_add_f32_e32 v46, 1.0, v48
	v_add_f32_e32 v47, 1.0, v49
	v_mul_f32_e32 v48, 0xbfb8aa3b, v34
	v_mul_f32_e32 v49, 0xbfb8aa3b, v35
	v_exp_f32_e32 v48, v48
	v_exp_f32_e32 v49, v49
	v_rcp_f32_e32 v46, v46
	v_rcp_f32_e32 v47, v47
	v_add_f32_e32 v48, 1.0, v48
	v_add_f32_e32 v49, 1.0, v49
	v_rcp_f32_e32 v48, v48
	v_rcp_f32_e32 v49, v49
	v_pk_mul_f32 v[32:33], v[32:33], v[46:47]
	v_pk_mul_f32 v[42:43], v[44:45], v[42:43]
	v_pk_mul_f32 v[36:37], v[32:33], v[36:37]
	v_pk_mul_f32 v[32:33], v[34:35], v[48:49]
	v_mul_f32_e32 v35, 0xbfb8aa3b, v28
	v_cvt_pk_bf16_f32 v34, v36, v37
	v_exp_f32_e32 v36, v35
	v_mul_f32_e32 v35, 0xbfb8aa3b, v29
	v_exp_f32_e32 v37, v35
	v_pk_mul_f32 v[38:39], v[32:33], v[38:39]
	v_cvt_pk_bf16_f32 v32, v40, v41
	v_cvt_pk_bf16_f32 v35, v38, v39
	v_add_co_u32_e32 v38, vcc, s0, v96
	v_cvt_pk_bf16_f32 v33, v42, v43
	v_add_f32_e32 v36, 1.0, v36
	v_add_f32_e32 v37, 1.0, v37
	v_addc_co_u32_e32 v39, vcc, 0, v97, vcc
	v_rcp_f32_e32 v36, v36
	v_rcp_f32_e32 v37, v37
	global_store_dwordx4 v[38:39], v[32:35], off
	v_pk_mul_f32 v[28:29], v[28:29], v[36:37]
	s_nop 0
	v_mul_f32_e32 v32, 0xbfb8aa3b, v30
	v_mul_f32_e32 v33, 0xbfb8aa3b, v31
	v_exp_f32_e32 v32, v32
	v_exp_f32_e32 v33, v33
	v_pk_mul_f32 v[24:25], v[28:29], v[24:25]
	v_add_f32_e32 v28, 1.0, v32
	v_add_f32_e32 v29, 1.0, v33
	v_mul_f32_e32 v32, 0xbfb8aa3b, v16
	v_mul_f32_e32 v33, 0xbfb8aa3b, v17
	v_rcp_f32_e32 v28, v28
	v_rcp_f32_e32 v29, v29
	v_exp_f32_e32 v32, v32
	v_exp_f32_e32 v33, v33
	v_pk_mul_f32 v[28:29], v[30:31], v[28:29]
	v_add_f32_e32 v30, 1.0, v32
	v_add_f32_e32 v31, 1.0, v33
	v_mul_f32_e32 v32, 0xbfb8aa3b, v18
	v_mul_f32_e32 v33, 0xbfb8aa3b, v19
	v_exp_f32_e32 v32, v32
	v_exp_f32_e32 v33, v33
	v_rcp_f32_e32 v30, v30
	v_rcp_f32_e32 v31, v31
	v_add_f32_e32 v32, 1.0, v32
	v_add_f32_e32 v33, 1.0, v33
	v_rcp_f32_e32 v32, v32
	v_rcp_f32_e32 v33, v33
	v_pk_mul_f32 v[16:17], v[16:17], v[30:31]
	v_pk_mul_f32 v[26:27], v[28:29], v[26:27]
	v_pk_mul_f32 v[20:21], v[16:17], v[20:21]
	v_pk_mul_f32 v[16:17], v[18:19], v[32:33]
	v_mul_f32_e32 v19, 0xbfb8aa3b, v12
	v_cvt_pk_bf16_f32 v18, v20, v21
	v_exp_f32_e32 v20, v19
	v_mul_f32_e32 v19, 0xbfb8aa3b, v13
	v_exp_f32_e32 v21, v19
	v_pk_mul_f32 v[22:23], v[16:17], v[22:23]
	v_cvt_pk_bf16_f32 v16, v24, v25
	v_cvt_pk_bf16_f32 v19, v22, v23
	v_add_co_u32_e32 v22, vcc, s0, v80
	v_cvt_pk_bf16_f32 v17, v26, v27
	v_add_f32_e32 v20, 1.0, v20
	v_add_f32_e32 v21, 1.0, v21
	v_addc_co_u32_e32 v23, vcc, 0, v81, vcc
	v_rcp_f32_e32 v20, v20
	v_rcp_f32_e32 v21, v21
	global_store_dwordx4 v[22:23], v[16:19], off
	v_pk_mul_f32 v[12:13], v[12:13], v[20:21]
	s_nop 0
	v_mul_f32_e32 v16, 0xbfb8aa3b, v14
	v_mul_f32_e32 v17, 0xbfb8aa3b, v15
	v_exp_f32_e32 v16, v16
	v_exp_f32_e32 v17, v17
	v_pk_mul_f32 v[8:9], v[12:13], v[8:9]
	v_add_f32_e32 v12, 1.0, v16
	v_add_f32_e32 v13, 1.0, v17
	v_mul_f32_e32 v16, 0xbfb8aa3b, v0
	v_mul_f32_e32 v17, 0xbfb8aa3b, v1
	v_rcp_f32_e32 v12, v12
	v_rcp_f32_e32 v13, v13
	v_exp_f32_e32 v16, v16
	v_exp_f32_e32 v17, v17
	v_pk_mul_f32 v[12:13], v[14:15], v[12:13]
	v_add_f32_e32 v14, 1.0, v16
	v_add_f32_e32 v15, 1.0, v17
	v_mul_f32_e32 v16, 0xbfb8aa3b, v2
	v_mul_f32_e32 v17, 0xbfb8aa3b, v3
	v_exp_f32_e32 v16, v16
	v_exp_f32_e32 v17, v17
	v_rcp_f32_e32 v14, v14
	v_rcp_f32_e32 v15, v15
	v_add_f32_e32 v16, 1.0, v16
	v_add_f32_e32 v17, 1.0, v17
	v_rcp_f32_e32 v16, v16
	v_rcp_f32_e32 v17, v17
	v_pk_mul_f32 v[0:1], v[0:1], v[14:15]
	v_pk_mul_f32 v[10:11], v[12:13], v[10:11]
	v_pk_mul_f32 v[4:5], v[0:1], v[4:5]
	v_pk_mul_f32 v[0:1], v[2:3], v[16:17]
	v_cvt_pk_bf16_f32 v2, v4, v5
	v_pk_mul_f32 v[6:7], v[0:1], v[6:7]
	v_add_co_u32_e32 v4, vcc, 0xb0000, v64
	v_cvt_pk_bf16_f32 v0, v8, v9
	v_cvt_pk_bf16_f32 v1, v10, v11
	v_cvt_pk_bf16_f32 v3, v6, v7
	v_addc_co_u32_e32 v5, vcc, 0, v65, vcc
	global_store_dwordx4 v[4:5], v[0:3], off
	s_cbranch_scc0 .LBB0_666
	s_branch .LP2_up2

.LP2_up2:
	s_lshl_b32 s0, s8, 3
	s_and_b32 s0, s0, 56
	s_bfe_u32 s1, s8, 0x30003
	v_mov_b32_e32 v134, v154
	s_or_b32 s12, s0, s1
	s_ashr_i32 s0, s8, 6
	v_ashrrev_i32_e32 v5, 6, v134
	v_lshrrev_b32_e32 v1, 4, v134
	v_ashrrev_i32_e32 v4, 3, v134
	v_lshrrev_b32_e32 v0, 2, v134
	v_and_b32_e32 v3, 3, v134
	s_lshl_b32 s1, s12, 19
	v_readlane_b32 s4, v253, 47
	v_bfi_b32 v0, -16, v4, v0
	v_lshlrev_b32_e32 v2, 5, v5
	v_bitop3_b32 v1, v1, v3, 2 bitop3:0x6c
	v_readlane_b32 s5, v253, 48
	s_add_u32 s6, s4, s1
	v_and_b32_e32 v2, 32, v2
	v_lshlrev_b32_e32 v3, 3, v1
	v_ashrrev_i32_e32 v1, 31, v0
	s_addc_u32 s7, s5, 0
	v_or_b32_e32 v11, v3, v2
	v_lshlrev_b64 v[0:1], 11, v[0:1]
	v_and_b32_e32 v9, 15, v134
	v_lshl_add_u64 v[6:7], s[6:7], 0, v[0:1]
	v_lshlrev_b32_e32 v136, 1, v11
	v_lshl_add_u64 v[128:129], v[6:7], 0, v[136:137]
	v_lshlrev_b32_e32 v6, 6, v9
	v_lshlrev_b32_e32 v9, 2, v134
	v_ashrrev_i32_e32 v8, 8, v134
	v_and_b32_e32 v10, 48, v134
	v_and_b32_e32 v9, 32, v9
	s_ashr_i32 s1, s0, 31
	v_or_b32_e32 v7, v6, v10
	v_bitop3_b32 v6, v6, v9, v10 bitop3:0x36
	v_lshlrev_b32_e32 v10, 13, v8
	v_lshlrev_b32_e32 v5, 12, v5
	s_lshl_b64 s[4:5], s[0:1], 19
	v_lshlrev_b32_e32 v146, 4, v134
	v_bitop3_b32 v144, v7, v10, v9 bitop3:0xde
	v_and_or_b32 v5, v5, s75, v6
	s_add_u32 s14, s9, s4
	v_add_u32_e32 v147, 0x10000, v146
	v_add_u32_e32 v135, 0x10000, v144
	v_or_b32_e32 v145, 0x8000, v5
	v_or_b32_e32 v139, 0x18000, v5
	s_addc_u32 s15, s10, s5
	v_lshl_add_u64 v[0:1], s[14:15], 0, v[0:1]
	v_add_u32_e32 v148, 0x8000, v146
	v_add_u32_e32 v149, 0xa000, v146
	v_readfirstlane_b32 s1, v148
	v_lshl_add_u64 v[0:1], v[0:1], 0, v[136:137]
	s_mov_b32 m0, s1
	s_mov_b64 s[6:7], 0x20000
	v_readfirstlane_b32 s1, v149
	v_lshl_add_u64 v[6:7], v[0:1], 0, s[6:7]
	s_mov_b32 m0, s1
	v_readfirstlane_b32 s1, v146
	v_add_u32_e32 v150, 0x2000, v146
	s_mov_b32 m0, s1
	v_readfirstlane_b32 s1, v150
	v_add_u32_e32 v151, 0xc000, v146
	v_lshl_add_u64 v[6:7], v[128:129], 0, s[6:7]
	s_mov_b32 m0, s1
	s_mov_b64 s[6:7], 0x40000
	v_readfirstlane_b32 s1, v151
	v_add_u32_e32 v152, 0xe000, v146
	v_lshl_add_u64 v[6:7], v[0:1], 0, s[6:7]
	s_mov_b32 m0, s1
	s_mov_b64 s[14:15], 0x60000
	v_readfirstlane_b32 s1, v152
	v_add_u32_e32 v153, 0x4000, v146
	v_lshl_add_u64 v[6:7], v[0:1], 0, s[14:15]
	s_mov_b32 m0, s1
	v_readfirstlane_b32 s1, v153
	v_add_u32_e32 v170, 0x6000, v146
	v_lshl_add_u64 v[6:7], v[128:129], 0, s[6:7]
	s_mov_b32 m0, s1
	v_readfirstlane_b32 s1, v170
	v_lshl_add_u64 v[6:7], v[128:129], 0, s[14:15]
	s_mov_b32 m0, s1
	v_cmp_eq_u32_e32 vcc, 1, v8
	s_and_saveexec_b64 s[6:7], vcc
	s_cbranch_execz .LP2_up2_662
	s_barrier
.LP2_up2_662:
	s_or_b64 exec, exec, s[6:7]
	s_lshr_b32 s1, s8, 3
	s_and_b32 s1, s1, 7
	s_lshl_b32 s6, s11, 19
	s_lshl_b32 s1, s1, 19
	s_and_b32 s6, s6, 0x1c00000
	v_add_u32_e32 v171, 0x8000, v147
	s_or_b32 s1, s6, s1
	s_mov_b64 s[14:15], 0x80
	v_readfirstlane_b32 s6, v171
	v_add_u32_e32 v172, 0xa000, v147
	v_and_b32_e32 v6, -16, v4
	v_lshl_add_u64 v[4:5], v[0:1], 0, s[14:15]
	s_mov_b32 m0, s6
	s_mov_b64 s[26:27], 0x20080
	v_readfirstlane_b32 s6, v172
	s_waitcnt vmcnt(20)
	s_barrier
	v_lshl_add_u64 v[4:5], v[0:1], 0, s[26:27]
	s_mov_b32 m0, s6
	v_readfirstlane_b32 s6, v147
	v_add_u32_e32 v173, 0x2000, v147
	v_lshl_add_u64 v[4:5], v[128:129], 0, s[14:15]
	s_mov_b32 m0, s6
	v_readfirstlane_b32 s6, v173
	v_lshl_add_u64 v[4:5], v[128:129], 0, s[26:27]
	s_mov_b32 m0, s6
	s_mov_b64 s[6:7], 0x40080
	v_add_u32_e32 v174, 0xc000, v147
	v_lshl_add_u64 v[4:5], v[0:1], 0, s[6:7]
	v_readfirstlane_b32 s6, v174
	s_mov_b32 m0, s6
	s_mov_b64 s[6:7], 0x60080
	v_add_u32_e32 v175, 0xe000, v147
	v_lshl_add_u64 v[0:1], v[0:1], 0, s[6:7]
	v_readfirstlane_b32 s6, v175
	s_mov_b32 m0, s6
	v_bfe_u32 v7, v134, 2, 4
	v_add_u32_e32 v0, v6, v7
	v_ashrrev_i32_e32 v1, 31, v0
	s_add_u32 s4, s21, s4
	v_lshlrev_b64 v[0:1], 11, v[0:1]
	s_addc_u32 s5, s22, s5
	v_lshl_add_u64 v[130:131], s[4:5], 0, v[0:1]
	s_add_u32 s4, s72, s1
	s_waitcnt vmcnt(16)
	s_addc_u32 s5, s73, 0
	v_lshl_add_u64 v[132:133], s[4:5], 0, v[0:1]
	v_mov_b32_e32 v0, 0
	v_add_lshl_u32 v136, v2, v3, 1
	s_mov_b32 s1, -2
	v_mov_b32_e32 v1, v0
	v_mov_b32_e32 v2, v0
	v_mov_b32_e32 v3, v0
	v_mov_b32_e32 v4, v0
	v_mov_b32_e32 v5, v0
	v_mov_b32_e32 v6, v0
	v_mov_b32_e32 v7, v0
	v_mov_b32_e32 v12, v0
	v_mov_b32_e32 v13, v0
	v_mov_b32_e32 v14, v0
	v_mov_b32_e32 v15, v0
	v_mov_b32_e32 v20, v0
	v_mov_b32_e32 v21, v0
	v_mov_b32_e32 v22, v0
	v_mov_b32_e32 v23, v0
	v_mov_b32_e32 v8, v0
	v_mov_b32_e32 v9, v0
	v_mov_b32_e32 v10, v0
	v_mov_b32_e32 v11, v0
	v_mov_b32_e32 v16, v0
	v_mov_b32_e32 v17, v0
	v_mov_b32_e32 v18, v0
	v_mov_b32_e32 v19, v0
	v_mov_b32_e32 v28, v0
	v_mov_b32_e32 v29, v0
	v_mov_b32_e32 v30, v0
	v_mov_b32_e32 v31, v0
	v_mov_b32_e32 v36, v0
	v_mov_b32_e32 v37, v0
	v_mov_b32_e32 v38, v0
	v_mov_b32_e32 v39, v0
	v_mov_b32_e32 v24, v0
	v_mov_b32_e32 v25, v0
	v_mov_b32_e32 v26, v0
	v_mov_b32_e32 v27, v0
	v_mov_b32_e32 v32, v0
	v_mov_b32_e32 v33, v0
	v_mov_b32_e32 v34, v0
	v_mov_b32_e32 v35, v0
	v_mov_b32_e32 v44, v0
	v_mov_b32_e32 v45, v0
	v_mov_b32_e32 v46, v0
	v_mov_b32_e32 v47, v0
	v_mov_b32_e32 v52, v0
	v_mov_b32_e32 v53, v0
	v_mov_b32_e32 v54, v0
	v_mov_b32_e32 v55, v0
	v_mov_b32_e32 v40, v0
	v_mov_b32_e32 v41, v0
	v_mov_b32_e32 v42, v0
	v_mov_b32_e32 v43, v0
	v_mov_b32_e32 v48, v0
	v_mov_b32_e32 v49, v0
	v_mov_b32_e32 v50, v0
	v_mov_b32_e32 v51, v0
	v_mov_b32_e32 v56, v0
	v_mov_b32_e32 v57, v0
	v_mov_b32_e32 v58, v0
	v_mov_b32_e32 v59, v0
	v_mov_b32_e32 v60, v0
	v_mov_b32_e32 v61, v0
	v_mov_b32_e32 v62, v0
	v_mov_b32_e32 v63, v0
	v_mov_b32_e32 v64, v0
	v_mov_b32_e32 v65, v0
	v_mov_b32_e32 v66, v0
	v_mov_b32_e32 v67, v0
	v_mov_b32_e32 v68, v0
	v_mov_b32_e32 v69, v0
	v_mov_b32_e32 v70, v0
	v_mov_b32_e32 v71, v0
	v_mov_b32_e32 v80, v0
	v_mov_b32_e32 v81, v0
	v_mov_b32_e32 v82, v0
	v_mov_b32_e32 v83, v0
	v_mov_b32_e32 v84, v0
	v_mov_b32_e32 v85, v0
	v_mov_b32_e32 v86, v0
	v_mov_b32_e32 v87, v0
	v_mov_b32_e32 v72, v0
	v_mov_b32_e32 v73, v0
	v_mov_b32_e32 v74, v0
	v_mov_b32_e32 v75, v0
	v_mov_b32_e32 v76, v0
	v_mov_b32_e32 v77, v0
	v_mov_b32_e32 v78, v0
	v_mov_b32_e32 v79, v0
	v_mov_b32_e32 v96, v0
	v_mov_b32_e32 v97, v0
	v_mov_b32_e32 v98, v0
	v_mov_b32_e32 v99, v0
	v_mov_b32_e32 v100, v0
	v_mov_b32_e32 v101, v0
	v_mov_b32_e32 v102, v0
	v_mov_b32_e32 v103, v0
	v_mov_b32_e32 v88, v0
	v_mov_b32_e32 v89, v0
	v_mov_b32_e32 v90, v0
	v_mov_b32_e32 v91, v0
	v_mov_b32_e32 v92, v0
	v_mov_b32_e32 v93, v0
	v_mov_b32_e32 v94, v0
	v_mov_b32_e32 v95, v0
	v_mov_b32_e32 v112, v0
	v_mov_b32_e32 v113, v0
	v_mov_b32_e32 v114, v0
	v_mov_b32_e32 v115, v0
	v_mov_b32_e32 v116, v0
	v_mov_b32_e32 v117, v0
	v_mov_b32_e32 v118, v0
	v_mov_b32_e32 v119, v0
	v_mov_b32_e32 v104, v0
	v_mov_b32_e32 v105, v0
	v_mov_b32_e32 v106, v0
	v_mov_b32_e32 v107, v0
	v_mov_b32_e32 v108, v0
	v_mov_b32_e32 v109, v0
	v_mov_b32_e32 v110, v0
	v_mov_b32_e32 v111, v0
	v_mov_b32_e32 v120, v0
	v_mov_b32_e32 v121, v0
	v_mov_b32_e32 v122, v0
	v_mov_b32_e32 v123, v0
	v_mov_b32_e32 v124, v0
	v_mov_b32_e32 v125, v0
	v_mov_b32_e32 v126, v0
	v_mov_b32_e32 v127, v0
	s_barrier
	ds_read_b128 v[140:143], v145
	ds_read_b128 v[162:165], v145 offset:1024
	ds_read_b128 v[178:181], v145 offset:2048
	ds_read_b128 v[182:185], v145 offset:3072
	v_add_u32_e32 v176, 0x4000, v147
	v_lshl_add_u64 v[234:235], v[132:133], 0, v[136:137]
	v_readfirstlane_b32 s4, v176
	v_add_u32_e32 v177, 0x6000, v147
	v_lshl_add_u64 v[218:219], v[234:235], 0, s[76:77]
	s_mov_b32 m0, s4
	v_readfirstlane_b32 s4, v177
	ds_read_b128 v[186:189], v144
	ds_read_b128 v[190:193], v144 offset:1024
	ds_read_b128 v[194:197], v144 offset:2048
	ds_read_b128 v[198:201], v144 offset:3072
	ds_read_b128 v[202:205], v144 offset:4096
	ds_read_b128 v[206:209], v144 offset:5120
	ds_read_b128 v[210:213], v144 offset:6144
	ds_read_b128 v[214:217], v144 offset:7168
	v_lshl_add_u64 v[218:219], v[234:235], 0, s[16:17]
	s_mov_b32 m0, s4
	s_nop 0
	s_waitcnt lgkmcnt(8)
	s_barrier
	s_waitcnt lgkmcnt(0)
	s_setprio 1
	s_waitcnt lgkmcnt(0)
	v_mfma_f32_16x16x32_bf16 v[124:127], v[140:143], v[186:189], v[124:127]
	v_mfma_f32_16x16x32_bf16 v[120:123], v[178:181], v[186:189], v[120:123]
	v_mfma_f32_16x16x32_bf16 v[116:119], v[140:143], v[194:197], v[116:119]
	v_mfma_f32_16x16x32_bf16 v[112:115], v[178:181], v[194:197], v[112:115]
	v_mfma_f32_16x16x32_bf16 v[100:103], v[140:143], v[202:205], v[100:103]
	v_mfma_f32_16x16x32_bf16 v[96:99], v[178:181], v[202:205], v[96:99]
	v_mfma_f32_16x16x32_bf16 v[84:87], v[140:143], v[210:213], v[84:87]
	v_mfma_f32_16x16x32_bf16 v[80:83], v[178:181], v[210:213], v[80:83]
	v_mfma_f32_16x16x32_bf16 v[124:127], v[162:165], v[190:193], v[124:127]
	v_mfma_f32_16x16x32_bf16 v[120:123], v[182:185], v[190:193], v[120:123]
	v_mfma_f32_16x16x32_bf16 v[116:119], v[162:165], v[198:201], v[116:119]
	v_mfma_f32_16x16x32_bf16 v[112:115], v[182:185], v[198:201], v[112:115]
	v_mfma_f32_16x16x32_bf16 v[100:103], v[162:165], v[206:209], v[100:103]
	v_mfma_f32_16x16x32_bf16 v[96:99], v[182:185], v[206:209], v[96:99]
	v_mfma_f32_16x16x32_bf16 v[84:87], v[162:165], v[214:217], v[84:87]
	v_mfma_f32_16x16x32_bf16 v[80:83], v[182:185], v[214:217], v[80:83]
	s_setprio 0
	s_barrier
	v_lshl_add_u64 v[236:237], v[130:131], 0, v[136:137]
	s_mov_b64 s[4:5], 0x2600100
	v_lshl_add_u64 v[238:239], v[236:237], 0, s[4:5]
	v_readfirstlane_b32 s4, v148
	s_mov_b32 m0, s4
	s_mov_b64 s[4:5], 0x2620100
	ds_read_b128 v[218:221], v145 offset:16384
	ds_read_b128 v[222:225], v145 offset:17408
	ds_read_b128 v[226:229], v145 offset:18432
	ds_read_b128 v[230:233], v145 offset:19456
	global_load_lds_dwordx4 v[238:239], off
	v_lshl_add_u64 v[238:239], v[236:237], 0, s[4:5]
	v_readfirstlane_b32 s4, v149
	s_mov_b32 m0, s4
	s_nop 0
	global_load_lds_dwordx4 v[238:239], off
	s_barrier
	s_waitcnt lgkmcnt(0)
	s_setprio 1
	s_waitcnt lgkmcnt(0)
	v_mfma_f32_16x16x32_bf16 v[108:111], v[218:221], v[186:189], v[108:111]
	v_mfma_f32_16x16x32_bf16 v[104:107], v[226:229], v[186:189], v[104:107]
	v_mfma_f32_16x16x32_bf16 v[92:95], v[218:221], v[194:197], v[92:95]
	v_mfma_f32_16x16x32_bf16 v[88:91], v[226:229], v[194:197], v[88:91]
	v_mfma_f32_16x16x32_bf16 v[76:79], v[218:221], v[202:205], v[76:79]
	v_mfma_f32_16x16x32_bf16 v[72:75], v[226:229], v[202:205], v[72:75]
	v_mfma_f32_16x16x32_bf16 v[68:71], v[218:221], v[210:213], v[68:71]
	v_mfma_f32_16x16x32_bf16 v[64:67], v[226:229], v[210:213], v[64:67]
	v_mfma_f32_16x16x32_bf16 v[108:111], v[222:225], v[190:193], v[108:111]
	v_mfma_f32_16x16x32_bf16 v[104:107], v[230:233], v[190:193], v[104:107]
	v_mfma_f32_16x16x32_bf16 v[92:95], v[222:225], v[198:201], v[92:95]
	v_mfma_f32_16x16x32_bf16 v[88:91], v[230:233], v[198:201], v[88:91]
	v_mfma_f32_16x16x32_bf16 v[76:79], v[222:225], v[206:209], v[76:79]
	v_mfma_f32_16x16x32_bf16 v[72:75], v[230:233], v[206:209], v[72:75]
	v_mfma_f32_16x16x32_bf16 v[68:71], v[222:225], v[214:217], v[68:71]
	v_mfma_f32_16x16x32_bf16 v[64:67], v[230:233], v[214:217], v[64:67]
	s_setprio 0
	v_readfirstlane_b32 s4, v146
	v_lshl_add_u64 v[238:239], v[234:235], 0, s[88:89]
	s_mov_b32 m0, s4
	v_readfirstlane_b32 s4, v150
	s_barrier
	ds_read_b128 v[186:189], v144 offset:16384
	ds_read_b128 v[190:193], v144 offset:17408
	ds_read_b128 v[194:197], v144 offset:18432
	ds_read_b128 v[198:201], v144 offset:19456
	ds_read_b128 v[202:205], v144 offset:20480
	ds_read_b128 v[206:209], v144 offset:21504
	ds_read_b128 v[210:213], v144 offset:22528
	ds_read_b128 v[214:217], v144 offset:23552
	global_load_lds_dwordx4 v[238:239], off
	v_lshl_add_u64 v[238:239], v[234:235], 0, s[90:91]
	s_mov_b32 m0, s4
	s_nop 0
	global_load_lds_dwordx4 v[238:239], off
	s_barrier
	s_waitcnt lgkmcnt(0)
	s_setprio 1
	s_waitcnt lgkmcnt(0)
	v_mfma_f32_16x16x32_bf16 v[60:63], v[140:143], v[186:189], v[60:63]
	v_mfma_f32_16x16x32_bf16 v[56:59], v[178:181], v[186:189], v[56:59]
	v_mfma_f32_16x16x32_bf16 v[52:55], v[140:143], v[194:197], v[52:55]
	v_mfma_f32_16x16x32_bf16 v[44:47], v[178:181], v[194:197], v[44:47]
	v_mfma_f32_16x16x32_bf16 v[36:39], v[140:143], v[202:205], v[36:39]
	v_mfma_f32_16x16x32_bf16 v[28:31], v[178:181], v[202:205], v[28:31]
	v_mfma_f32_16x16x32_bf16 v[20:23], v[140:143], v[210:213], v[20:23]
	v_mfma_f32_16x16x32_bf16 v[12:15], v[178:181], v[210:213], v[12:15]
	v_mfma_f32_16x16x32_bf16 v[60:63], v[162:165], v[190:193], v[60:63]
	v_mfma_f32_16x16x32_bf16 v[56:59], v[182:185], v[190:193], v[56:59]
	v_mfma_f32_16x16x32_bf16 v[52:55], v[162:165], v[198:201], v[52:55]
	v_mfma_f32_16x16x32_bf16 v[44:47], v[182:185], v[198:201], v[44:47]
	v_mfma_f32_16x16x32_bf16 v[36:39], v[162:165], v[206:209], v[36:39]
	v_mfma_f32_16x16x32_bf16 v[28:31], v[182:185], v[206:209], v[28:31]
	v_mfma_f32_16x16x32_bf16 v[20:23], v[162:165], v[214:217], v[20:23]
	v_mfma_f32_16x16x32_bf16 v[12:15], v[182:185], v[214:217], v[12:15]
	s_setprio 0
	s_barrier
	s_mov_b64 s[4:5], 0x2640100
	v_lshl_add_u64 v[140:141], v[236:237], 0, s[4:5]
	v_readfirstlane_b32 s4, v151
	s_mov_b32 m0, s4
	s_mov_b64 s[4:5], 0x2660100
	global_load_lds_dwordx4 v[140:141], off
	v_lshl_add_u64 v[140:141], v[236:237], 0, s[4:5]
	v_readfirstlane_b32 s4, v152
	s_mov_b32 m0, s4
	s_nop 0
	global_load_lds_dwordx4 v[140:141], off
	s_waitcnt vmcnt(14)
	s_barrier
	s_setprio 1
	v_mfma_f32_16x16x32_bf16 v[48:51], v[218:221], v[186:189], v[48:51]
	v_mfma_f32_16x16x32_bf16 v[40:43], v[226:229], v[186:189], v[40:43]
	v_mfma_f32_16x16x32_bf16 v[32:35], v[218:221], v[194:197], v[32:35]
	v_mfma_f32_16x16x32_bf16 v[24:27], v[226:229], v[194:197], v[24:27]
	v_mfma_f32_16x16x32_bf16 v[16:19], v[218:221], v[202:205], v[16:19]
	v_mfma_f32_16x16x32_bf16 v[8:11], v[226:229], v[202:205], v[8:11]
	v_mfma_f32_16x16x32_bf16 v[4:7], v[218:221], v[210:213], v[4:7]
	v_mfma_f32_16x16x32_bf16 v[0:3], v[226:229], v[210:213], v[0:3]
	v_mfma_f32_16x16x32_bf16 v[48:51], v[222:225], v[190:193], v[48:51]
	v_mfma_f32_16x16x32_bf16 v[40:43], v[230:233], v[190:193], v[40:43]
	v_mfma_f32_16x16x32_bf16 v[32:35], v[222:225], v[198:201], v[32:35]
	v_mfma_f32_16x16x32_bf16 v[24:27], v[230:233], v[198:201], v[24:27]
	v_mfma_f32_16x16x32_bf16 v[16:19], v[222:225], v[206:209], v[16:19]
	v_mfma_f32_16x16x32_bf16 v[8:11], v[230:233], v[206:209], v[8:11]
	v_mfma_f32_16x16x32_bf16 v[4:7], v[222:225], v[214:217], v[4:7]
	v_mfma_f32_16x16x32_bf16 v[0:3], v[230:233], v[214:217], v[0:3]
	s_setprio 0
	s_barrier
	ds_read_b128 v[140:143], v139
	ds_read_b128 v[162:165], v139 offset:1024
	ds_read_b128 v[178:181], v139 offset:2048
	ds_read_b128 v[182:185], v139 offset:3072
	v_readfirstlane_b32 s4, v153
	v_lshl_add_u64 v[218:219], v[234:235], 0, s[94:95]
	s_mov_b32 m0, s4
	v_readfirstlane_b32 s4, v170
	ds_read_b128 v[186:189], v135
	ds_read_b128 v[190:193], v135 offset:1024
	ds_read_b128 v[194:197], v135 offset:2048
	ds_read_b128 v[198:201], v135 offset:3072
	ds_read_b128 v[202:205], v135 offset:4096
	ds_read_b128 v[206:209], v135 offset:5120
	ds_read_b128 v[210:213], v135 offset:6144
	ds_read_b128 v[214:217], v135 offset:7168
	global_load_lds_dwordx4 v[218:219], off
	v_lshl_add_u64 v[218:219], v[234:235], 0, s[78:79]
	s_mov_b32 m0, s4
	s_nop 0
	global_load_lds_dwordx4 v[218:219], off
	s_waitcnt lgkmcnt(8)
	s_barrier
	s_waitcnt lgkmcnt(0)
	s_setprio 1
	s_waitcnt lgkmcnt(0)
	v_mfma_f32_16x16x32_bf16 v[124:127], v[140:143], v[186:189], v[124:127]
	v_mfma_f32_16x16x32_bf16 v[120:123], v[178:181], v[186:189], v[120:123]
	v_mfma_f32_16x16x32_bf16 v[116:119], v[140:143], v[194:197], v[116:119]
	v_mfma_f32_16x16x32_bf16 v[112:115], v[178:181], v[194:197], v[112:115]
	v_mfma_f32_16x16x32_bf16 v[100:103], v[140:143], v[202:205], v[100:103]
	v_mfma_f32_16x16x32_bf16 v[96:99], v[178:181], v[202:205], v[96:99]
	v_mfma_f32_16x16x32_bf16 v[84:87], v[140:143], v[210:213], v[84:87]
	v_mfma_f32_16x16x32_bf16 v[80:83], v[178:181], v[210:213], v[80:83]
	v_mfma_f32_16x16x32_bf16 v[124:127], v[162:165], v[190:193], v[124:127]
	v_mfma_f32_16x16x32_bf16 v[120:123], v[182:185], v[190:193], v[120:123]
	v_mfma_f32_16x16x32_bf16 v[116:119], v[162:165], v[198:201], v[116:119]
	v_mfma_f32_16x16x32_bf16 v[112:115], v[182:185], v[198:201], v[112:115]
	v_mfma_f32_16x16x32_bf16 v[100:103], v[162:165], v[206:209], v[100:103]
	v_mfma_f32_16x16x32_bf16 v[96:99], v[182:185], v[206:209], v[96:99]
	v_mfma_f32_16x16x32_bf16 v[84:87], v[162:165], v[214:217], v[84:87]
	v_mfma_f32_16x16x32_bf16 v[80:83], v[182:185], v[214:217], v[80:83]
	s_setprio 0
	s_barrier
	s_mov_b64 s[4:5], 0x2600180
	v_lshl_add_u64 v[238:239], v[236:237], 0, s[4:5]
	v_readfirstlane_b32 s4, v171
	s_mov_b32 m0, s4
	s_mov_b64 s[4:5], 0x2620180
	ds_read_b128 v[218:221], v139 offset:16384
	ds_read_b128 v[222:225], v139 offset:17408
	ds_read_b128 v[226:229], v139 offset:18432
	ds_read_b128 v[230:233], v139 offset:19456
	global_load_lds_dwordx4 v[238:239], off
	v_lshl_add_u64 v[238:239], v[236:237], 0, s[4:5]
	v_readfirstlane_b32 s4, v172
	s_mov_b32 m0, s4
	s_nop 0
	global_load_lds_dwordx4 v[238:239], off
	s_barrier
	s_waitcnt lgkmcnt(0)
	s_setprio 1
	s_waitcnt lgkmcnt(0)
	v_mfma_f32_16x16x32_bf16 v[108:111], v[218:221], v[186:189], v[108:111]
	v_mfma_f32_16x16x32_bf16 v[104:107], v[226:229], v[186:189], v[104:107]
	v_mfma_f32_16x16x32_bf16 v[92:95], v[218:221], v[194:197], v[92:95]
	v_mfma_f32_16x16x32_bf16 v[88:91], v[226:229], v[194:197], v[88:91]
	v_mfma_f32_16x16x32_bf16 v[76:79], v[218:221], v[202:205], v[76:79]
	v_mfma_f32_16x16x32_bf16 v[72:75], v[226:229], v[202:205], v[72:75]
	v_mfma_f32_16x16x32_bf16 v[68:71], v[218:221], v[210:213], v[68:71]
	v_mfma_f32_16x16x32_bf16 v[64:67], v[226:229], v[210:213], v[64:67]
	v_mfma_f32_16x16x32_bf16 v[108:111], v[222:225], v[190:193], v[108:111]
	v_mfma_f32_16x16x32_bf16 v[104:107], v[230:233], v[190:193], v[104:107]
	v_mfma_f32_16x16x32_bf16 v[92:95], v[222:225], v[198:201], v[92:95]
	v_mfma_f32_16x16x32_bf16 v[88:91], v[230:233], v[198:201], v[88:91]
	v_mfma_f32_16x16x32_bf16 v[76:79], v[222:225], v[206:209], v[76:79]
	v_mfma_f32_16x16x32_bf16 v[72:75], v[230:233], v[206:209], v[72:75]
	v_mfma_f32_16x16x32_bf16 v[68:71], v[222:225], v[214:217], v[68:71]
	v_mfma_f32_16x16x32_bf16 v[64:67], v[230:233], v[214:217], v[64:67]
	s_setprio 0
	v_readfirstlane_b32 s4, v147
	v_lshl_add_u64 v[238:239], v[234:235], 0, s[24:25]
	s_mov_b32 m0, s4
	v_readfirstlane_b32 s4, v173
	s_barrier
	ds_read_b128 v[186:189], v135 offset:16384
	ds_read_b128 v[190:193], v135 offset:17408
	ds_read_b128 v[194:197], v135 offset:18432
	ds_read_b128 v[198:201], v135 offset:19456
	ds_read_b128 v[202:205], v135 offset:20480
	ds_read_b128 v[206:209], v135 offset:21504
	ds_read_b128 v[210:213], v135 offset:22528
	ds_read_b128 v[214:217], v135 offset:23552
	global_load_lds_dwordx4 v[238:239], off
	v_lshl_add_u64 v[234:235], v[234:235], 0, s[28:29]
	s_mov_b32 m0, s4
	s_nop 0
	global_load_lds_dwordx4 v[234:235], off
	s_barrier
	s_waitcnt lgkmcnt(0)
	s_setprio 1
	s_waitcnt lgkmcnt(0)
	v_mfma_f32_16x16x32_bf16 v[60:63], v[140:143], v[186:189], v[60:63]
	v_mfma_f32_16x16x32_bf16 v[56:59], v[178:181], v[186:189], v[56:59]
	v_mfma_f32_16x16x32_bf16 v[52:55], v[140:143], v[194:197], v[52:55]
	v_mfma_f32_16x16x32_bf16 v[44:47], v[178:181], v[194:197], v[44:47]
	v_mfma_f32_16x16x32_bf16 v[36:39], v[140:143], v[202:205], v[36:39]
	v_mfma_f32_16x16x32_bf16 v[28:31], v[178:181], v[202:205], v[28:31]
	v_mfma_f32_16x16x32_bf16 v[20:23], v[140:143], v[210:213], v[20:23]
	v_mfma_f32_16x16x32_bf16 v[12:15], v[178:181], v[210:213], v[12:15]
	v_mfma_f32_16x16x32_bf16 v[60:63], v[162:165], v[190:193], v[60:63]
	v_mfma_f32_16x16x32_bf16 v[56:59], v[182:185], v[190:193], v[56:59]
	v_mfma_f32_16x16x32_bf16 v[52:55], v[162:165], v[198:201], v[52:55]
	v_mfma_f32_16x16x32_bf16 v[44:47], v[182:185], v[198:201], v[44:47]
	v_mfma_f32_16x16x32_bf16 v[36:39], v[162:165], v[206:209], v[36:39]
	v_mfma_f32_16x16x32_bf16 v[28:31], v[182:185], v[206:209], v[28:31]
	v_mfma_f32_16x16x32_bf16 v[20:23], v[162:165], v[214:217], v[20:23]
	v_mfma_f32_16x16x32_bf16 v[12:15], v[182:185], v[214:217], v[12:15]
	s_setprio 0
	s_barrier
	s_mov_b64 s[4:5], 0x2640180
	v_lshl_add_u64 v[140:141], v[236:237], 0, s[4:5]
	v_readfirstlane_b32 s4, v174
	s_mov_b32 m0, s4
	s_mov_b64 s[4:5], 0x2660180
	global_load_lds_dwordx4 v[140:141], off
	v_lshl_add_u64 v[140:141], v[236:237], 0, s[4:5]
	v_readfirstlane_b32 s4, v175
	s_mov_b32 m0, s4
	s_nop 0
	global_load_lds_dwordx4 v[140:141], off
	s_waitcnt vmcnt(6)
	s_barrier
	s_setprio 1
	v_mfma_f32_16x16x32_bf16 v[48:51], v[218:221], v[186:189], v[48:51]
	v_mfma_f32_16x16x32_bf16 v[40:43], v[226:229], v[186:189], v[40:43]
	v_mfma_f32_16x16x32_bf16 v[32:35], v[218:221], v[194:197], v[32:35]
	v_mfma_f32_16x16x32_bf16 v[24:27], v[226:229], v[194:197], v[24:27]
	v_mfma_f32_16x16x32_bf16 v[16:19], v[218:221], v[202:205], v[16:19]
	v_mfma_f32_16x16x32_bf16 v[8:11], v[226:229], v[202:205], v[8:11]
	v_mfma_f32_16x16x32_bf16 v[4:7], v[218:221], v[210:213], v[4:7]
	v_mfma_f32_16x16x32_bf16 v[0:3], v[226:229], v[210:213], v[0:3]
	v_mfma_f32_16x16x32_bf16 v[48:51], v[222:225], v[190:193], v[48:51]
	v_mfma_f32_16x16x32_bf16 v[40:43], v[230:233], v[190:193], v[40:43]
	v_mfma_f32_16x16x32_bf16 v[32:35], v[222:225], v[198:201], v[32:35]
	v_mfma_f32_16x16x32_bf16 v[24:27], v[230:233], v[198:201], v[24:27]
	v_mfma_f32_16x16x32_bf16 v[16:19], v[222:225], v[206:209], v[16:19]
	v_mfma_f32_16x16x32_bf16 v[8:11], v[230:233], v[206:209], v[8:11]
	v_mfma_f32_16x16x32_bf16 v[4:7], v[222:225], v[214:217], v[4:7]
	v_mfma_f32_16x16x32_bf16 v[0:3], v[230:233], v[214:217], v[0:3]
	s_setprio 0
	s_add_i32 s1, s1, 2
	v_lshl_add_u64 v[130:131], v[130:131], 0, s[86:87]
	s_cmp_gt_u32 s1, 11
	v_lshl_add_u64 v[132:133], v[132:133], 0, s[86:87]
	s_barrier
	s_branch .LBB0_663
